# loop-edge rotation: counter/pointer/exit-test SALU moved in front of the loop-back barrier in the six GEMM K-loops and both diff tile-loop copies
# speedup vs baseline: 1.0021x; 1.0021x over previous
; #define PG8_STAGE(bufoff, gbase, voff) do { _Pragma("unroll") for (int _i = 0; _i < 2; ++_i) \
;         __builtin_amdgcn_global_load_lds((const unsigned*)((const char*)(gbase) + (voff)[_i]), (LAS unsigned*)(lds + (bufoff) + ldsw + _i * 8192), 16, 0, 0); } while (0)
; #define PG8_LDA(dst, b, h) do { _Pragma("unroll") for (int m = 0; m < 4; ++m) _Pragma("unroll") for (int k = 0; k < 2; ++k) dst[m][k] = *(const LAS bf16x8*)(lds + PG8_SA(b, h) + aoff + m * 2048 + k * 1024); } while (0)
; #define PG8_LDB(dst, b, h) do { _Pragma("unroll") for (int n = 0; n < 2; ++n) _Pragma("unroll") for (int k = 0; k < 2; ++k) dst[n][k] = *(const LAS bf16x8*)(lds + PG8_SB(b, h) + boff + n * 2048 + k * 1024); } while (0)
; #define PG8_MMA(ai, bj, At, Bt) do { __builtin_amdgcn_s_setprio(1); _Pragma("unroll") for (int m = 0; m < 4; ++m) _Pragma("unroll") for (int n = 0; n < 2; ++n) _Pragma("unroll") for (int k = 0; k < 2; ++k) \
;         acc[ai][bj][m][n] = __builtin_amdgcn_mfma_f32_16x16x32_bf16(Bt[n][k], At[m][k], acc[ai][bj][m][n], 0, 0, 0); __builtin_amdgcn_s_setprio(0); } while (0)
; #define PG8_WAIT_V(n) asm volatile("s_waitcnt vmcnt(" #n ")" ::: "memory")
; #define PG8_WAIT_L(n) asm volatile("s_waitcnt lgkmcnt(" #n ")" ::: "memory")
; #define PG8_BAR __builtin_amdgcn_s_barrier()
; #define PG8_SCHED __builtin_amdgcn_sched_barrier(0)
; template <class Epi>
; __device__ __forceinline__ void gemm_phase(LAS unsigned char* lds, const Gemm g, const StaticOrder& S, const Epi& E, const int wid) {
;     ...
;         for (int t = 0; t < nt; t += 2) {
;             const bool last = (t == nt - 2);
;             const char* a1 = cA + (size_t)(t + 1) * kstep;
;             const char* a2 = last ? nA : cA + (size_t)(t + 2) * kstep; const char* b2 = last ? nB : cB + (size_t)(t + 2) * kstep;
;             const char* a3 = a2 + kstep; const char* b3 = b2 + kstep;
;             PG8_LDB(B0, 0, 0); PG8_LDB(B1, 0, 1); PG8_SCHED; PG8_LDA(At, 0, 0); PG8_STAGE(PG8_SA(1, 1), a1 + hstepA, voffA);
;             PG8_WAIT_V(8); PG8_WAIT_L(0); PG8_BAR; PG8_MMA(0, 0, At, B0); PG8_MMA(0, 1, At, B1); PG8_BAR; PG8_SCHED;
;             PG8_LDA(At, 0, 1); PG8_STAGE(PG8_SB(0, 0), b2, voffB); PG8_STAGE(PG8_SB(0, 1), b2 + hstepB, voffB); PG8_STAGE(PG8_SA(0, 0), a2, voffA);
;             PG8_WAIT_V(8); PG8_WAIT_L(0); PG8_BAR; PG8_MMA(1, 0, At, B0); PG8_MMA(1, 1, At, B1); PG8_BAR; PG8_SCHED;
.LBB0_157:
	ds_read_b128 v[150:153], v157
	ds_read_b128 v[160:163], v157 offset:1024
	ds_read_b128 v[164:167], v157 offset:2048
	ds_read_b128 v[168:171], v157 offset:3072
	ds_read_b128 v[172:175], v158
	ds_read_b128 v[176:179], v158 offset:1024
	ds_read_b128 v[180:183], v158 offset:2048
	ds_read_b128 v[184:187], v158 offset:3072
	s_add_u32 s8, s10, 0x100
	s_addc_u32 s9, s11, 0
	s_cmp_eq_u32 s60, 28
	s_cselect_b32 s59, s51, s9
	s_cselect_b32 s58, s50, s8
	s_cselect_b32 s57, s20, s55
	s_cselect_b32 s56, s21, s49
	s_add_i32 m0, s0, 0xc000
	ds_read_b128 v[188:191], v159
	global_load_lds_dwordx4 v142, s[10:11]
	s_add_i32 m0, s0, 0xe000
	ds_read_b128 v[192:195], v159 offset:1024
	global_load_lds_dwordx4 v144, s[10:11]
	ds_read_b128 v[196:199], v159 offset:2048
	ds_read_b128 v[200:203], v159 offset:3072
	ds_read_b128 v[204:207], v159 offset:4096
	ds_read_b128 v[208:211], v159 offset:5120
	ds_read_b128 v[212:215], v159 offset:6144
	ds_read_b128 v[216:219], v159 offset:7168
	s_waitcnt vmcnt(8)
	s_waitcnt lgkmcnt(0)
	s_barrier
	s_setprio 1
	s_waitcnt lgkmcnt(0)
	v_mfma_f32_16x16x32_bf16 v[124:127], v[150:153], v[188:191], v[124:127]
	v_mfma_f32_16x16x32_bf16 v[120:123], v[164:167], v[188:191], v[120:123]
	v_mfma_f32_16x16x32_bf16 v[116:119], v[150:153], v[196:199], v[116:119]
	v_mfma_f32_16x16x32_bf16 v[112:115], v[164:167], v[196:199], v[112:115]
	v_mfma_f32_16x16x32_bf16 v[108:111], v[150:153], v[204:207], v[108:111]
	v_mfma_f32_16x16x32_bf16 v[104:107], v[164:167], v[204:207], v[104:107]
	v_mfma_f32_16x16x32_bf16 v[100:103], v[150:153], v[212:215], v[100:103]
	v_mfma_f32_16x16x32_bf16 v[96:99], v[164:167], v[212:215], v[96:99]
	v_mfma_f32_16x16x32_bf16 v[124:127], v[160:163], v[192:195], v[124:127]
	v_mfma_f32_16x16x32_bf16 v[120:123], v[168:171], v[192:195], v[120:123]
	v_mfma_f32_16x16x32_bf16 v[116:119], v[160:163], v[200:203], v[116:119]
	v_mfma_f32_16x16x32_bf16 v[112:115], v[168:171], v[200:203], v[112:115]
	v_mfma_f32_16x16x32_bf16 v[108:111], v[160:163], v[208:211], v[108:111]
	v_mfma_f32_16x16x32_bf16 v[104:107], v[168:171], v[208:211], v[104:107]
	v_mfma_f32_16x16x32_bf16 v[100:103], v[160:163], v[216:219], v[100:103]
	v_mfma_f32_16x16x32_bf16 v[96:99], v[168:171], v[216:219], v[96:99]
	s_setprio 0
	s_setprio 1
	v_mfma_f32_16x16x32_bf16 v[60:63], v[172:175], v[188:191], v[60:63]
	v_mfma_f32_16x16x32_bf16 v[56:59], v[180:183], v[188:191], v[56:59]
	v_mfma_f32_16x16x32_bf16 v[52:55], v[172:175], v[196:199], v[52:55]
	v_mfma_f32_16x16x32_bf16 v[48:51], v[180:183], v[196:199], v[48:51]
	v_mfma_f32_16x16x32_bf16 v[44:47], v[172:175], v[204:207], v[44:47]
	v_mfma_f32_16x16x32_bf16 v[40:43], v[180:183], v[204:207], v[40:43]
	v_mfma_f32_16x16x32_bf16 v[36:39], v[172:175], v[212:215], v[36:39]
	v_mfma_f32_16x16x32_bf16 v[32:35], v[180:183], v[212:215], v[32:35]
	v_mfma_f32_16x16x32_bf16 v[60:63], v[176:179], v[192:195], v[60:63]
	v_mfma_f32_16x16x32_bf16 v[56:59], v[184:187], v[192:195], v[56:59]
	v_mfma_f32_16x16x32_bf16 v[52:55], v[176:179], v[200:203], v[52:55]
	v_mfma_f32_16x16x32_bf16 v[48:51], v[184:187], v[200:203], v[48:51]
	v_mfma_f32_16x16x32_bf16 v[44:47], v[176:179], v[208:211], v[44:47]
	v_mfma_f32_16x16x32_bf16 v[40:43], v[184:187], v[208:211], v[40:43]
	v_mfma_f32_16x16x32_bf16 v[36:39], v[176:179], v[216:219], v[36:39]
	v_mfma_f32_16x16x32_bf16 v[32:35], v[184:187], v[216:219], v[32:35]
	s_setprio 0
	s_barrier
	s_add_i32 s10, s68, s94
	s_mov_b32 m0, s10
	ds_read_b128 v[188:191], v159 offset:16384
	global_load_lds_dwordx4 v130, s[56:57]
	s_add_i32 m0, s10, 0x2000
	s_add_u32 s10, s56, 0x80000
	s_addc_u32 s11, s57, 0
	s_add_i32 s24, s69, s94
	global_load_lds_dwordx4 v134, s[56:57]
	s_mov_b32 m0, s24
	ds_read_b128 v[192:195], v159 offset:17408
	global_load_lds_dwordx4 v130, s[10:11]
	s_add_i32 m0, s24, 0x2000
	ds_read_b128 v[196:199], v159 offset:18432
	global_load_lds_dwordx4 v134, s[10:11]
	s_mov_b32 m0, s0
	ds_read_b128 v[200:203], v159 offset:19456
	global_load_lds_dwordx4 v128, s[58:59]
	s_mov_b32 m0, s1
	ds_read_b128 v[204:207], v159 offset:20480
	global_load_lds_dwordx4 v132, s[58:59]
	ds_read_b128 v[208:211], v159 offset:21504
	ds_read_b128 v[212:215], v159 offset:22528
	ds_read_b128 v[216:219], v159 offset:23552
	s_waitcnt vmcnt(8)
	s_waitcnt lgkmcnt(0)
	s_barrier
	s_setprio 1
	s_waitcnt lgkmcnt(0)
	v_mfma_f32_16x16x32_bf16 v[92:95], v[150:153], v[188:191], v[92:95]
	v_mfma_f32_16x16x32_bf16 v[88:91], v[164:167], v[188:191], v[88:91]
	v_mfma_f32_16x16x32_bf16 v[84:87], v[150:153], v[196:199], v[84:87]
	v_mfma_f32_16x16x32_bf16 v[80:83], v[164:167], v[196:199], v[80:83]
	v_mfma_f32_16x16x32_bf16 v[76:79], v[150:153], v[204:207], v[76:79]
	v_mfma_f32_16x16x32_bf16 v[72:75], v[164:167], v[204:207], v[72:75]
	v_mfma_f32_16x16x32_bf16 v[68:71], v[150:153], v[212:215], v[68:71]
	v_mfma_f32_16x16x32_bf16 v[64:67], v[164:167], v[212:215], v[64:67]
	v_mfma_f32_16x16x32_bf16 v[92:95], v[160:163], v[192:195], v[92:95]
	v_mfma_f32_16x16x32_bf16 v[88:91], v[168:171], v[192:195], v[88:91]
	v_mfma_f32_16x16x32_bf16 v[84:87], v[160:163], v[200:203], v[84:87]
	v_mfma_f32_16x16x32_bf16 v[80:83], v[168:171], v[200:203], v[80:83]
	v_mfma_f32_16x16x32_bf16 v[76:79], v[160:163], v[208:211], v[76:79]
	v_mfma_f32_16x16x32_bf16 v[72:75], v[168:171], v[208:211], v[72:75]
	v_mfma_f32_16x16x32_bf16 v[68:71], v[160:163], v[216:219], v[68:71]
	v_mfma_f32_16x16x32_bf16 v[64:67], v[168:171], v[216:219], v[64:67]
	s_setprio 0
	s_setprio 1
	v_mfma_f32_16x16x32_bf16 v[28:31], v[172:175], v[188:191], v[28:31]
	v_mfma_f32_16x16x32_bf16 v[24:27], v[180:183], v[188:191], v[24:27]
	v_mfma_f32_16x16x32_bf16 v[20:23], v[172:175], v[196:199], v[20:23]
	v_mfma_f32_16x16x32_bf16 v[16:19], v[180:183], v[196:199], v[16:19]
	v_mfma_f32_16x16x32_bf16 v[12:15], v[172:175], v[204:207], v[12:15]
	v_mfma_f32_16x16x32_bf16 v[8:11], v[180:183], v[204:207], v[8:11]
	v_mfma_f32_16x16x32_bf16 v[4:7], v[172:175], v[212:215], v[4:7]
	v_mfma_f32_16x16x32_bf16 v[0:3], v[180:183], v[212:215], v[0:3]
	v_mfma_f32_16x16x32_bf16 v[28:31], v[176:179], v[192:195], v[28:31]
	v_mfma_f32_16x16x32_bf16 v[24:27], v[184:187], v[192:195], v[24:27]
	v_mfma_f32_16x16x32_bf16 v[20:23], v[176:179], v[200:203], v[20:23]
	v_mfma_f32_16x16x32_bf16 v[16:19], v[184:187], v[200:203], v[16:19]
	v_mfma_f32_16x16x32_bf16 v[12:15], v[176:179], v[208:211], v[12:15]
	v_mfma_f32_16x16x32_bf16 v[8:11], v[184:187], v[208:211], v[8:11]
	v_mfma_f32_16x16x32_bf16 v[4:7], v[176:179], v[216:219], v[4:7]
	v_mfma_f32_16x16x32_bf16 v[0:3], v[184:187], v[216:219], v[0:3]
	s_setprio 0
	s_barrier
; #define PG8_STAGE(bufoff, gbase, voff) do { _Pragma("unroll") for (int _i = 0; _i < 2; ++_i) \
;         __builtin_amdgcn_global_load_lds((const unsigned*)((const char*)(gbase) + (voff)[_i]), (LAS unsigned*)(lds + (bufoff) + ldsw + _i * 8192), 16, 0, 0); } while (0)
; #define PG8_LDA(dst, b, h) do { _Pragma("unroll") for (int m = 0; m < 4; ++m) _Pragma("unroll") for (int k = 0; k < 2; ++k) dst[m][k] = *(const LAS bf16x8*)(lds + PG8_SA(b, h) + aoff + m * 2048 + k * 1024); } while (0)
; #define PG8_LDB(dst, b, h) do { _Pragma("unroll") for (int n = 0; n < 2; ++n) _Pragma("unroll") for (int k = 0; k < 2; ++k) dst[n][k] = *(const LAS bf16x8*)(lds + PG8_SB(b, h) + boff + n * 2048 + k * 1024); } while (0)
; #define PG8_MMA(ai, bj, At, Bt) do { __builtin_amdgcn_s_setprio(1); _Pragma("unroll") for (int m = 0; m < 4; ++m) _Pragma("unroll") for (int n = 0; n < 2; ++n) _Pragma("unroll") for (int k = 0; k < 2; ++k) \
;         acc[ai][bj][m][n] = __builtin_amdgcn_mfma_f32_16x16x32_bf16(Bt[n][k], At[m][k], acc[ai][bj][m][n], 0, 0, 0); __builtin_amdgcn_s_setprio(0); } while (0)
; #define PG8_WAIT_V(n) asm volatile("s_waitcnt vmcnt(" #n ")" ::: "memory")
; #define PG8_WAIT_L(n) asm volatile("s_waitcnt lgkmcnt(" #n ")" ::: "memory")
; #define PG8_BAR __builtin_amdgcn_s_barrier()
; #define PG8_SCHED __builtin_amdgcn_sched_barrier(0)
; template <class Epi>
; __device__ __forceinline__ void gemm_phase(LAS unsigned char* lds, const Gemm g, const StaticOrder& S, const Epi& E, const int wid) {
;     ...
;             PG8_LDB(B0, 1, 0); PG8_LDB(B1, 1, 1); PG8_SCHED; PG8_LDA(At, 1, 0); PG8_STAGE(PG8_SA(0, 1), a2 + hstepA, voffA);
;             PG8_WAIT_V(8); PG8_WAIT_L(0); PG8_BAR; PG8_MMA(0, 0, At, B0); PG8_MMA(0, 1, At, B1); PG8_BAR; PG8_SCHED;
;             PG8_LDA(At, 1, 1); PG8_STAGE(PG8_SB(1, 0), b3, voffB); PG8_STAGE(PG8_SB(1, 1), b3 + hstepB, voffB); PG8_STAGE(PG8_SA(1, 0), a3, voffA);
;             PG8_WAIT_V(8); PG8_WAIT_L(0); PG8_BAR; PG8_MMA(1, 0, At, B0); PG8_MMA(1, 1, At, B1); PG8_BAR; PG8_SCHED;
;         }
	s_add_i32 s24, 0, 0x18000
	v_add_u32_e32 v136, s24, v139
	s_add_i32 s25, 0, 0x1c000
	ds_read_b128 v[150:153], v136
	ds_read_b128 v[160:163], v136 offset:1024
	ds_read_b128 v[164:167], v136 offset:2048
	ds_read_b128 v[168:171], v136 offset:3072
	v_add_u32_e32 v136, s25, v139
	ds_read_b128 v[172:175], v136
	ds_read_b128 v[176:179], v136 offset:1024
	ds_read_b128 v[180:183], v136 offset:2048
	ds_read_b128 v[184:187], v136 offset:3072
	s_add_u32 s10, s58, 0x80000
	s_addc_u32 s11, s59, 0
	s_mov_b32 m0, s15
	ds_read_b128 v[188:191], v159 offset:32768
	global_load_lds_dwordx4 v128, s[10:11]
	s_mov_b32 m0, s26
	ds_read_b128 v[192:195], v159 offset:33792
	global_load_lds_dwordx4 v132, s[10:11]
	ds_read_b128 v[196:199], v159 offset:34816
	ds_read_b128 v[200:203], v159 offset:35840
	ds_read_b128 v[204:207], v159 offset:36864
	ds_read_b128 v[208:211], v159 offset:37888
	ds_read_b128 v[212:215], v159 offset:38912
	ds_read_b128 v[216:219], v159 offset:39936
	s_waitcnt vmcnt(8)
	s_waitcnt lgkmcnt(0)
	s_barrier
	s_setprio 1
	s_waitcnt lgkmcnt(0)
	v_mfma_f32_16x16x32_bf16 v[124:127], v[150:153], v[188:191], v[124:127]
	v_mfma_f32_16x16x32_bf16 v[120:123], v[164:167], v[188:191], v[120:123]
	v_mfma_f32_16x16x32_bf16 v[116:119], v[150:153], v[196:199], v[116:119]
	v_mfma_f32_16x16x32_bf16 v[112:115], v[164:167], v[196:199], v[112:115]
	v_mfma_f32_16x16x32_bf16 v[108:111], v[150:153], v[204:207], v[108:111]
	v_mfma_f32_16x16x32_bf16 v[104:107], v[164:167], v[204:207], v[104:107]
	v_mfma_f32_16x16x32_bf16 v[100:103], v[150:153], v[212:215], v[100:103]
	v_mfma_f32_16x16x32_bf16 v[96:99], v[164:167], v[212:215], v[96:99]
	v_mfma_f32_16x16x32_bf16 v[124:127], v[160:163], v[192:195], v[124:127]
	v_mfma_f32_16x16x32_bf16 v[120:123], v[168:171], v[192:195], v[120:123]
	v_mfma_f32_16x16x32_bf16 v[116:119], v[160:163], v[200:203], v[116:119]
	v_mfma_f32_16x16x32_bf16 v[112:115], v[168:171], v[200:203], v[112:115]
	v_mfma_f32_16x16x32_bf16 v[108:111], v[160:163], v[208:211], v[108:111]
	v_mfma_f32_16x16x32_bf16 v[104:107], v[168:171], v[208:211], v[104:107]
	v_mfma_f32_16x16x32_bf16 v[100:103], v[160:163], v[216:219], v[100:103]
	v_mfma_f32_16x16x32_bf16 v[96:99], v[168:171], v[216:219], v[96:99]
	s_setprio 0
	s_setprio 1
	v_mfma_f32_16x16x32_bf16 v[60:63], v[172:175], v[188:191], v[60:63]
	v_mfma_f32_16x16x32_bf16 v[56:59], v[180:183], v[188:191], v[56:59]
	v_mfma_f32_16x16x32_bf16 v[52:55], v[172:175], v[196:199], v[52:55]
	v_mfma_f32_16x16x32_bf16 v[48:51], v[180:183], v[196:199], v[48:51]
	v_mfma_f32_16x16x32_bf16 v[44:47], v[172:175], v[204:207], v[44:47]
	v_mfma_f32_16x16x32_bf16 v[40:43], v[180:183], v[204:207], v[40:43]
	v_mfma_f32_16x16x32_bf16 v[36:39], v[172:175], v[212:215], v[36:39]
	v_mfma_f32_16x16x32_bf16 v[32:35], v[180:183], v[212:215], v[32:35]
	v_mfma_f32_16x16x32_bf16 v[60:63], v[176:179], v[192:195], v[60:63]
	v_mfma_f32_16x16x32_bf16 v[56:59], v[184:187], v[192:195], v[56:59]
	v_mfma_f32_16x16x32_bf16 v[52:55], v[176:179], v[200:203], v[52:55]
	v_mfma_f32_16x16x32_bf16 v[48:51], v[184:187], v[200:203], v[48:51]
	v_mfma_f32_16x16x32_bf16 v[44:47], v[176:179], v[208:211], v[44:47]
	v_mfma_f32_16x16x32_bf16 v[40:43], v[184:187], v[208:211], v[40:43]
	v_mfma_f32_16x16x32_bf16 v[36:39], v[176:179], v[216:219], v[36:39]
	v_mfma_f32_16x16x32_bf16 v[32:35], v[184:187], v[216:219], v[32:35]
	s_setprio 0
	s_barrier
	s_add_i32 s10, s24, s94
	s_add_u32 s98, s56, 0x80
	s_addc_u32 s99, s57, 0
	s_mov_b32 m0, s10
	ds_read_b128 v[188:191], v159 offset:49152
	global_load_lds_dwordx4 v130, s[98:99]
	s_add_i32 m0, s10, 0x2000
	s_add_u32 s10, s56, 0x80080
	s_addc_u32 s11, s57, 0
	s_add_i32 s24, s25, s94
	global_load_lds_dwordx4 v134, s[98:99]
	s_mov_b32 m0, s24
	ds_read_b128 v[192:195], v159 offset:50176
	global_load_lds_dwordx4 v130, s[10:11]
	s_add_i32 m0, s24, 0x2000
	ds_read_b128 v[196:199], v159 offset:51200
	global_load_lds_dwordx4 v134, s[10:11]
	s_add_u32 s100, s58, 0x80
	s_addc_u32 s101, s59, 0
	s_mov_b32 m0, s66
	ds_read_b128 v[200:203], v159 offset:52224
	global_load_lds_dwordx4 v128, s[100:101]
	s_mov_b32 m0, s67
	ds_read_b128 v[204:207], v159 offset:53248
	global_load_lds_dwordx4 v132, s[100:101]
	ds_read_b128 v[208:211], v159 offset:54272
	ds_read_b128 v[212:215], v159 offset:55296
	ds_read_b128 v[216:219], v159 offset:56320
	s_waitcnt vmcnt(8)
	s_waitcnt lgkmcnt(0)
	s_barrier
	s_setprio 1
	s_waitcnt lgkmcnt(0)
	v_mfma_f32_16x16x32_bf16 v[92:95], v[150:153], v[188:191], v[92:95]
	v_mfma_f32_16x16x32_bf16 v[88:91], v[164:167], v[188:191], v[88:91]
	v_mfma_f32_16x16x32_bf16 v[84:87], v[150:153], v[196:199], v[84:87]
	v_mfma_f32_16x16x32_bf16 v[80:83], v[164:167], v[196:199], v[80:83]
	v_mfma_f32_16x16x32_bf16 v[76:79], v[150:153], v[204:207], v[76:79]
	v_mfma_f32_16x16x32_bf16 v[72:75], v[164:167], v[204:207], v[72:75]
	v_mfma_f32_16x16x32_bf16 v[68:71], v[150:153], v[212:215], v[68:71]
	v_mfma_f32_16x16x32_bf16 v[64:67], v[164:167], v[212:215], v[64:67]
	v_mfma_f32_16x16x32_bf16 v[92:95], v[160:163], v[192:195], v[92:95]
	v_mfma_f32_16x16x32_bf16 v[88:91], v[168:171], v[192:195], v[88:91]
	v_mfma_f32_16x16x32_bf16 v[84:87], v[160:163], v[200:203], v[84:87]
	v_mfma_f32_16x16x32_bf16 v[80:83], v[168:171], v[200:203], v[80:83]
	v_mfma_f32_16x16x32_bf16 v[76:79], v[160:163], v[208:211], v[76:79]
	v_mfma_f32_16x16x32_bf16 v[72:75], v[168:171], v[208:211], v[72:75]
	v_mfma_f32_16x16x32_bf16 v[68:71], v[160:163], v[216:219], v[68:71]
	v_mfma_f32_16x16x32_bf16 v[64:67], v[168:171], v[216:219], v[64:67]
	s_setprio 0
	s_setprio 1
	v_mfma_f32_16x16x32_bf16 v[28:31], v[172:175], v[188:191], v[28:31]
	v_mfma_f32_16x16x32_bf16 v[24:27], v[180:183], v[188:191], v[24:27]
	v_mfma_f32_16x16x32_bf16 v[20:23], v[172:175], v[196:199], v[20:23]
	v_mfma_f32_16x16x32_bf16 v[16:19], v[180:183], v[196:199], v[16:19]
	v_mfma_f32_16x16x32_bf16 v[12:15], v[172:175], v[204:207], v[12:15]
	v_mfma_f32_16x16x32_bf16 v[8:11], v[180:183], v[204:207], v[8:11]
	v_mfma_f32_16x16x32_bf16 v[4:7], v[172:175], v[212:215], v[4:7]
	v_mfma_f32_16x16x32_bf16 v[0:3], v[180:183], v[212:215], v[0:3]
	v_mfma_f32_16x16x32_bf16 v[28:31], v[176:179], v[192:195], v[28:31]
	v_mfma_f32_16x16x32_bf16 v[24:27], v[184:187], v[192:195], v[24:27]
	v_mfma_f32_16x16x32_bf16 v[20:23], v[176:179], v[200:203], v[20:23]
	v_mfma_f32_16x16x32_bf16 v[16:19], v[184:187], v[200:203], v[16:19]
	v_mfma_f32_16x16x32_bf16 v[12:15], v[176:179], v[208:211], v[12:15]
	v_mfma_f32_16x16x32_bf16 v[8:11], v[184:187], v[208:211], v[8:11]
	v_mfma_f32_16x16x32_bf16 v[4:7], v[176:179], v[216:219], v[4:7]
	v_mfma_f32_16x16x32_bf16 v[0:3], v[184:187], v[216:219], v[0:3]
	s_setprio 0
	s_add_i32 s60, s60, 2
	s_add_u32 s49, s49, 0x100
	s_addc_u32 s55, s55, 0
	s_cmp_gt_u32 s60, 29
	s_mov_b64 s[10:11], s[8:9]
	s_barrier
	s_cbranch_scc0 .LBB0_157
	s_and_b64 vcc, exec, s[22:23]
	s_cbranch_vccz .LBB0_160
	s_barrier

; __device__ __forceinline__ void partialSM(f32x16& p0, f32x16& p1, float& m_reg, float& mn, float& alpha) {
;     ...
;     constexpr float C2 = 1.4426950408889634f * SM_SCALE;
;     if (__builtin_expect(__all((pmax - m_reg) * SM_SCALE <= THR), 1)) { mn = m_reg; alpha = 1.f; }
;     else { mn = fmaxf(m_reg, pmax); alpha = __builtin_amdgcn_exp2f((m_reg - mn) * C2); m_reg = mn; }
;     const float mnL = -mn * C2;
; #pragma unroll
;     for (int r = 0; r < 16; ++r) p0[r] = fmaf(p0[r], C2, mnL);
; #pragma unroll
;     for (int r = 0; r < 16; ++r) p1[r] = fmaf(p1[r], C2, mnL);
; #pragma unroll
;     for (int r = 0; r < 16; ++r) p0[r] = __builtin_amdgcn_exp2f(p0[r]);
; }
; __device__ __forceinline__ void finishSM(f32x16& p0, f32x16& p1, float alpha, float& l_reg, bf16x8& pa0, bf16x8& pa1, bf16x8& pa2, bf16x8& pa3) {
; #pragma unroll
;     for (int r = 0; r < 16; ++r) p1[r] = __builtin_amdgcn_exp2f(p1[r]);
;     float ps = 0;
; #pragma unroll
;     for (int r = 0; r < 16; ++r) ps += p0[r];
; #pragma unroll
;     for (int r = 0; r < 16; ++r) ps += p1[r];
;     { auto rr = __builtin_amdgcn_permlane32_swap(__float_as_uint(ps), __float_as_uint(ps), false, false);
;       ps = __uint_as_float(rr[0]) + __uint_as_float(rr[1]); }
;     l_reg = l_reg * alpha + ps;
;     PK4(p0, 0, pa0); PK4(p0, 8, pa1); PK4(p1, 0, pa2); PK4(p1, 8, pa3);
; __device__ __forceinline__ void pv_tile2(f32x16* o, f32x16* o2, int vb0, bf16x8 pa0, bf16x8 pa1, bf16x8 pa2, bf16x8 pa3) {
.Ldu_join_e:
	v_mul_f32_e32 v2, 0xbe0293ee, v249
	v_fmamk_f32 v3, v160, 0x3e0293ee, v2
	v_fmamk_f32 v4, v161, 0x3e0293ee, v2
	v_exp_f32_e32 v3, v3
	v_fmamk_f32 v5, v162, 0x3e0293ee, v2
	v_exp_f32_e32 v4, v4
	v_fmamk_f32 v6, v163, 0x3e0293ee, v2
	v_exp_f32_e32 v5, v5
	v_fmamk_f32 v7, v164, 0x3e0293ee, v2
	v_fmamk_f32 v8, v165, 0x3e0293ee, v2
	v_fmamk_f32 v9, v166, 0x3e0293ee, v2
	v_fmamk_f32 v10, v167, 0x3e0293ee, v2
	v_fmamk_f32 v11, v168, 0x3e0293ee, v2
	v_fmamk_f32 v12, v169, 0x3e0293ee, v2
	v_fmamk_f32 v13, v170, 0x3e0293ee, v2
	v_fmamk_f32 v14, v171, 0x3e0293ee, v2
	v_fmamk_f32 v15, v172, 0x3e0293ee, v2
	v_fmamk_f32 v160, v173, 0x3e0293ee, v2
	v_fmamk_f32 v161, v174, 0x3e0293ee, v2
	v_fmamk_f32 v162, v175, 0x3e0293ee, v2
	v_fmamk_f32 v144, v144, 0x3e0293ee, v2
	v_fmamk_f32 v145, v145, 0x3e0293ee, v2
	v_fmamk_f32 v146, v146, 0x3e0293ee, v2
	v_fmamk_f32 v147, v147, 0x3e0293ee, v2
	v_fmamk_f32 v148, v148, 0x3e0293ee, v2
	v_fmamk_f32 v149, v149, 0x3e0293ee, v2
	v_fmamk_f32 v150, v150, 0x3e0293ee, v2
	v_fmamk_f32 v151, v151, 0x3e0293ee, v2
	v_fmamk_f32 v152, v152, 0x3e0293ee, v2
	v_fmamk_f32 v153, v153, 0x3e0293ee, v2
	v_fmamk_f32 v154, v154, 0x3e0293ee, v2
	v_fmamk_f32 v155, v155, 0x3e0293ee, v2
	v_fmamk_f32 v156, v156, 0x3e0293ee, v2
	v_fmamk_f32 v157, v157, 0x3e0293ee, v2
	v_fmamk_f32 v158, v158, 0x3e0293ee, v2
	v_fmac_f32_e32 v2, 0x3e0293ee, v159
	v_exp_f32_e32 v159, v6
	v_exp_f32_e32 v163, v7
	v_exp_f32_e32 v165, v2
	v_add_f32_e32 v2, 0, v3
	v_exp_f32_e32 v8, v8
	v_add_f32_e32 v2, v4, v2
	v_exp_f32_e32 v9, v9
	v_add_f32_e32 v2, v5, v2
	v_exp_f32_e32 v10, v10
	v_add_f32_e32 v2, v159, v2
	v_exp_f32_e32 v11, v11
	v_add_f32_e32 v2, v163, v2
	v_exp_f32_e32 v12, v12
	v_add_f32_e32 v2, v8, v2
	v_exp_f32_e32 v13, v13
	v_add_f32_e32 v2, v9, v2
	v_exp_f32_e32 v164, v14
	v_add_f32_e32 v2, v10, v2
	v_exp_f32_e32 v15, v15
	v_add_f32_e32 v2, v11, v2
	v_exp_f32_e32 v160, v160
	v_add_f32_e32 v2, v12, v2
	v_exp_f32_e32 v161, v161
	v_add_f32_e32 v2, v13, v2
	v_exp_f32_e32 v162, v162
	v_add_f32_e32 v2, v164, v2
	v_exp_f32_e32 v144, v144
	v_add_f32_e32 v2, v15, v2
	v_exp_f32_e32 v145, v145
	v_add_f32_e32 v2, v160, v2
	v_exp_f32_e32 v146, v146
	v_add_f32_e32 v2, v161, v2
	v_exp_f32_e32 v147, v147
	v_add_f32_e32 v2, v162, v2
	v_exp_f32_e32 v148, v148
	v_add_f32_e32 v2, v144, v2
	v_exp_f32_e32 v149, v149
	v_add_f32_e32 v2, v145, v2
	v_exp_f32_e32 v150, v150
	v_add_f32_e32 v2, v146, v2
	v_exp_f32_e32 v151, v151
	v_add_f32_e32 v2, v147, v2
	v_exp_f32_e32 v152, v152
	v_add_f32_e32 v2, v148, v2
	v_exp_f32_e32 v153, v153
	v_add_f32_e32 v2, v149, v2
	v_exp_f32_e32 v154, v154
	v_add_f32_e32 v2, v150, v2
	v_exp_f32_e32 v155, v155
	v_add_f32_e32 v2, v151, v2
	v_exp_f32_e32 v156, v156
	v_add_f32_e32 v2, v152, v2
	v_exp_f32_e32 v157, v157
	v_add_f32_e32 v2, v153, v2
	v_exp_f32_e32 v158, v158
	v_add_f32_e32 v2, v154, v2
	v_add_f32_e32 v2, v155, v2
	v_add_f32_e32 v2, v156, v2
	v_add_f32_e32 v2, v157, v2
	v_add_f32_e32 v2, v158, v2
	v_add_f32_e32 v2, v165, v2
	v_mov_b32_e32 v6, v2
	s_nop 1
	v_permlane32_swap_b32_e32 v2, v6
	v_add_f32_e32 v14, v2, v6
	v_fma_f32 v250, v250, v0, v14
	v_cvt_pk_bf16_f32 v6, v3, v4
	v_cvt_pk_bf16_f32 v7, v5, v159
	v_cvt_pk_bf16_f32 v8, v163, v8
	v_cvt_pk_bf16_f32 v9, v9, v10
	v_cvt_pk_bf16_f32 v10, v11, v12
	v_cvt_pk_bf16_f32 v11, v13, v164
	v_cvt_pk_bf16_f32 v12, v15, v160
	v_cvt_pk_bf16_f32 v13, v161, v162
	v_cvt_pk_bf16_f32 v144, v144, v145
	v_cvt_pk_bf16_f32 v145, v146, v147
	v_cvt_pk_bf16_f32 v146, v148, v149
	v_cvt_pk_bf16_f32 v147, v150, v151
	v_cvt_pk_bf16_f32 v2, v152, v153
	v_cvt_pk_bf16_f32 v3, v154, v155
	v_cvt_pk_bf16_f32 v4, v156, v157
	v_cvt_pk_bf16_f32 v5, v158, v165
	s_nop 0
	v_permlane32_swap_b32_e32 v6, v8
	v_permlane32_swap_b32_e32 v7, v9
	v_permlane32_swap_b32_e32 v10, v12
	v_permlane32_swap_b32_e32 v11, v13
	v_permlane32_swap_b32_e32 v144, v146
	v_permlane32_swap_b32_e32 v145, v147
	v_permlane32_swap_b32_e32 v2, v4
	v_permlane32_swap_b32_e32 v3, v5
	ds_read_b64_tr_b16 v[148:149], v246 offset:0x0
	ds_read_b64_tr_b16 v[150:151], v246 offset:0x800
	ds_read_b64_tr_b16 v[152:153], v246 offset:0x4000
	ds_read_b64_tr_b16 v[154:155], v246 offset:0x4800
	ds_read_b64_tr_b16 v[156:157], v246 offset:0x1000
	ds_read_b64_tr_b16 v[158:159], v246 offset:0x1800
	ds_read_b64_tr_b16 v[160:161], v246 offset:0x5000
	ds_read_b64_tr_b16 v[162:163], v246 offset:0x5800
	ds_read_b64_tr_b16 v[164:165], v246 offset:0x2000
	ds_read_b64_tr_b16 v[166:167], v246 offset:0x2800
	ds_read_b64_tr_b16 v[168:169], v246 offset:0x6000
	ds_read_b64_tr_b16 v[170:171], v246 offset:0x6800
	ds_read_b64_tr_b16 v[172:173], v246 offset:0x3000
	ds_read_b64_tr_b16 v[174:175], v246 offset:0x3800
	ds_read_b64_tr_b16 v[176:177], v246 offset:0x7000
	ds_read_b64_tr_b16 v[178:179], v246 offset:0x7800
	s_waitcnt lgkmcnt(0)
; #define A3_BAR() do { asm volatile("s_waitcnt vmcnt(0) lgkmcnt(0)" ::: "memory"); __builtin_amdgcn_s_barrier(); asm volatile("" ::: "memory"); } while (0)
; __device__ __forceinline__ void pv_tile2(f32x16* o, f32x16* o2, int vb0, bf16x8 pa0, bf16x8 pa1, bf16x8 pa2, bf16x8 pa3) {
;     ...
;     PV2_D0(0); PV2_D0(1); PV2_D0(2); PV2_D0(3);
; __device__ __forceinline__ void attn_block3(const BlockRef& cur, char* lds, const int wid) {
;     ...
;         pv_tile2(o, o2, vbase + (t & 1) * 2 * SHM_V, pa0, pa1, pa2, pa3);
;         A3_BAR();
	s_nop 0
	v_mfma_f32_32x32x16_bf16 v[112:127], v[6:9], v[148:151], v[112:127]
	ds_read_b64_tr_b16 v[148:149], v246 offset:0x200
	ds_read_b64_tr_b16 v[150:151], v246 offset:0xa00
	v_mfma_f32_32x32x16_bf16 v[128:143], v[6:9], v[152:155], v[128:143]
	ds_read_b64_tr_b16 v[152:153], v246 offset:0x4200
	ds_read_b64_tr_b16 v[154:155], v246 offset:0x4a00
	v_mfma_f32_32x32x16_bf16 v[112:127], v[10:13], v[156:159], v[112:127]
	ds_read_b64_tr_b16 v[156:157], v246 offset:0x1200
	ds_read_b64_tr_b16 v[158:159], v246 offset:0x1a00
	v_mfma_f32_32x32x16_bf16 v[128:143], v[10:13], v[160:163], v[128:143]
	ds_read_b64_tr_b16 v[160:161], v246 offset:0x5200
	ds_read_b64_tr_b16 v[162:163], v246 offset:0x5a00
	v_mfma_f32_32x32x16_bf16 v[112:127], v[144:147], v[164:167], v[112:127]
	ds_read_b64_tr_b16 v[164:165], v246 offset:0x2200
	ds_read_b64_tr_b16 v[166:167], v246 offset:0x2a00
	v_mfma_f32_32x32x16_bf16 v[128:143], v[144:147], v[168:171], v[128:143]
	ds_read_b64_tr_b16 v[168:169], v246 offset:0x6200
	ds_read_b64_tr_b16 v[170:171], v246 offset:0x6a00
	v_mfma_f32_32x32x16_bf16 v[112:127], v[2:5], v[172:175], v[112:127]
	ds_read_b64_tr_b16 v[172:173], v246 offset:0x3200
	ds_read_b64_tr_b16 v[174:175], v246 offset:0x3a00
	v_mfma_f32_32x32x16_bf16 v[128:143], v[2:5], v[176:179], v[128:143]
	ds_read_b64_tr_b16 v[176:177], v246 offset:0x7200
	ds_read_b64_tr_b16 v[178:179], v246 offset:0x7a00
	s_waitcnt lgkmcnt(0)
	v_mfma_f32_32x32x16_bf16 v[80:95], v[6:9], v[148:151], v[80:95]
	ds_read_b64_tr_b16 v[148:149], v246 offset:0x400
	ds_read_b64_tr_b16 v[150:151], v246 offset:0xc00
	v_mfma_f32_32x32x16_bf16 v[96:111], v[6:9], v[152:155], v[96:111]
	ds_read_b64_tr_b16 v[152:153], v246 offset:0x4400
	ds_read_b64_tr_b16 v[154:155], v246 offset:0x4c00
	v_mfma_f32_32x32x16_bf16 v[80:95], v[10:13], v[156:159], v[80:95]
	ds_read_b64_tr_b16 v[156:157], v246 offset:0x1400
	ds_read_b64_tr_b16 v[158:159], v246 offset:0x1c00
	v_mfma_f32_32x32x16_bf16 v[96:111], v[10:13], v[160:163], v[96:111]
	ds_read_b64_tr_b16 v[160:161], v246 offset:0x5400
	ds_read_b64_tr_b16 v[162:163], v246 offset:0x5c00
	v_mfma_f32_32x32x16_bf16 v[80:95], v[144:147], v[164:167], v[80:95]
	ds_read_b64_tr_b16 v[164:165], v246 offset:0x2400
	ds_read_b64_tr_b16 v[166:167], v246 offset:0x2c00
	v_mfma_f32_32x32x16_bf16 v[96:111], v[144:147], v[168:171], v[96:111]
	ds_read_b64_tr_b16 v[168:169], v246 offset:0x6400
	ds_read_b64_tr_b16 v[170:171], v246 offset:0x6c00
	v_mfma_f32_32x32x16_bf16 v[80:95], v[2:5], v[172:175], v[80:95]
	ds_read_b64_tr_b16 v[172:173], v246 offset:0x3400
	ds_read_b64_tr_b16 v[174:175], v246 offset:0x3c00
	v_mfma_f32_32x32x16_bf16 v[96:111], v[2:5], v[176:179], v[96:111]
	ds_read_b64_tr_b16 v[176:177], v246 offset:0x7400
	ds_read_b64_tr_b16 v[178:179], v246 offset:0x7c00
	s_waitcnt lgkmcnt(0)
	v_mfma_f32_32x32x16_bf16 v[48:63], v[6:9], v[148:151], v[48:63]
	ds_read_b64_tr_b16 v[148:149], v246 offset:0x600
	ds_read_b64_tr_b16 v[150:151], v246 offset:0xe00
	v_mfma_f32_32x32x16_bf16 v[64:79], v[6:9], v[152:155], v[64:79]
	ds_read_b64_tr_b16 v[152:153], v246 offset:0x4600
	ds_read_b64_tr_b16 v[154:155], v246 offset:0x4e00
	v_mfma_f32_32x32x16_bf16 v[48:63], v[10:13], v[156:159], v[48:63]
	ds_read_b64_tr_b16 v[156:157], v246 offset:0x1600
	ds_read_b64_tr_b16 v[158:159], v246 offset:0x1e00
	v_mfma_f32_32x32x16_bf16 v[64:79], v[10:13], v[160:163], v[64:79]
	ds_read_b64_tr_b16 v[160:161], v246 offset:0x5600
	ds_read_b64_tr_b16 v[162:163], v246 offset:0x5e00
	v_mfma_f32_32x32x16_bf16 v[48:63], v[144:147], v[164:167], v[48:63]
	ds_read_b64_tr_b16 v[164:165], v246 offset:0x2600
	ds_read_b64_tr_b16 v[166:167], v246 offset:0x2e00
	v_mfma_f32_32x32x16_bf16 v[64:79], v[144:147], v[168:171], v[64:79]
	ds_read_b64_tr_b16 v[168:169], v246 offset:0x6600
	ds_read_b64_tr_b16 v[170:171], v246 offset:0x6e00
	v_mfma_f32_32x32x16_bf16 v[48:63], v[2:5], v[172:175], v[48:63]
	ds_read_b64_tr_b16 v[172:173], v246 offset:0x3600
	ds_read_b64_tr_b16 v[174:175], v246 offset:0x3e00
	v_mfma_f32_32x32x16_bf16 v[64:79], v[2:5], v[176:179], v[64:79]
	ds_read_b64_tr_b16 v[176:177], v246 offset:0x7600
	ds_read_b64_tr_b16 v[178:179], v246 offset:0x7e00
	s_waitcnt lgkmcnt(0)
	v_mfma_f32_32x32x16_bf16 v[16:31], v[6:9], v[148:151], v[16:31]
	s_add_u32 s68, s68, 0x4000
	s_addc_u32 s69, s69, 0
	s_add_u32 s98, s98, 0x4000
	s_addc_u32 s99, s99, 0
	s_add_u32 s100, s100, 0x4000
	s_addc_u32 s101, s101, 0
	s_add_i32 s90, s90, 64
	s_waitcnt vmcnt(0) lgkmcnt(0)
	s_barrier
	v_add_u32_e32 v247, 0xffffff00, v247
	v_mfma_f32_32x32x16_bf16 v[32:47], v[6:9], v[152:155], v[32:47]
	v_subrev_u32_e32 v248, 64, v248
	s_cmp_eq_u32 s88, s93
	v_mfma_f32_32x32x16_bf16 v[16:31], v[10:13], v[156:159], v[16:31]
	v_mfma_f32_32x32x16_bf16 v[32:47], v[10:13], v[160:163], v[32:47]
	v_mfma_f32_32x32x16_bf16 v[16:31], v[144:147], v[164:167], v[16:31]
	v_mfma_f32_32x32x16_bf16 v[32:47], v[144:147], v[168:171], v[32:47]
	v_mfma_f32_32x32x16_bf16 v[16:31], v[2:5], v[172:175], v[16:31]
	v_mfma_f32_32x32x16_bf16 v[32:47], v[2:5], v[176:179], v[32:47]
	s_cbranch_scc1 .LBB0_491
	s_branch .Ldu_odd

; __device__ __forceinline__ void partialSM(f32x16& p0, f32x16& p1, float& m_reg, float& mn, float& alpha) {
;     ...
;     const float mnL = -mn * C2;
; #pragma unroll
;     for (int r = 0; r < 16; ++r) p0[r] = fmaf(p0[r], C2, mnL);
; #pragma unroll
;     for (int r = 0; r < 16; ++r) p1[r] = fmaf(p1[r], C2, mnL);
; #pragma unroll
;     for (int r = 0; r < 16; ++r) p0[r] = __builtin_amdgcn_exp2f(p0[r]);
; }
; __device__ __forceinline__ void finishSM(f32x16& p0, f32x16& p1, float alpha, float& l_reg, bf16x8& pa0, bf16x8& pa1, bf16x8& pa2, bf16x8& pa3) {
; #pragma unroll
;     for (int r = 0; r < 16; ++r) p1[r] = __builtin_amdgcn_exp2f(p1[r]);
;     float ps = 0;
; #pragma unroll
;     for (int r = 0; r < 16; ++r) ps += p0[r];
; #pragma unroll
;     for (int r = 0; r < 16; ++r) ps += p1[r];
;     { auto rr = __builtin_amdgcn_permlane32_swap(__float_as_uint(ps), __float_as_uint(ps), false, false);
;       ps = __uint_as_float(rr[0]) + __uint_as_float(rr[1]); }
;     l_reg = l_reg * alpha + ps;
;     PK4(p0, 0, pa0); PK4(p0, 8, pa1); PK4(p1, 0, pa2); PK4(p1, 8, pa3);
.Ldu_join_o:
	v_mul_f32_e32 v2, 0xbe0293ee, v249
	v_fmamk_f32 v3, v160, 0x3e0293ee, v2
	v_fmamk_f32 v4, v161, 0x3e0293ee, v2
	v_exp_f32_e32 v3, v3
	v_fmamk_f32 v5, v162, 0x3e0293ee, v2
	v_exp_f32_e32 v4, v4
	v_fmamk_f32 v6, v163, 0x3e0293ee, v2
	v_exp_f32_e32 v5, v5
	v_fmamk_f32 v7, v164, 0x3e0293ee, v2
	v_fmamk_f32 v8, v165, 0x3e0293ee, v2
	v_fmamk_f32 v9, v166, 0x3e0293ee, v2
	v_fmamk_f32 v10, v167, 0x3e0293ee, v2
	v_fmamk_f32 v11, v168, 0x3e0293ee, v2
	v_fmamk_f32 v12, v169, 0x3e0293ee, v2
	v_fmamk_f32 v13, v170, 0x3e0293ee, v2
	v_fmamk_f32 v14, v171, 0x3e0293ee, v2
	v_fmamk_f32 v15, v172, 0x3e0293ee, v2
	v_fmamk_f32 v160, v173, 0x3e0293ee, v2
	v_fmamk_f32 v161, v174, 0x3e0293ee, v2
	v_fmamk_f32 v162, v175, 0x3e0293ee, v2
	v_fmamk_f32 v144, v144, 0x3e0293ee, v2
	v_fmamk_f32 v145, v145, 0x3e0293ee, v2
	v_fmamk_f32 v146, v146, 0x3e0293ee, v2
	v_fmamk_f32 v147, v147, 0x3e0293ee, v2
	v_fmamk_f32 v148, v148, 0x3e0293ee, v2
	v_fmamk_f32 v149, v149, 0x3e0293ee, v2
	v_fmamk_f32 v150, v150, 0x3e0293ee, v2
	v_fmamk_f32 v151, v151, 0x3e0293ee, v2
	v_fmamk_f32 v152, v152, 0x3e0293ee, v2
	v_fmamk_f32 v153, v153, 0x3e0293ee, v2
	v_fmamk_f32 v154, v154, 0x3e0293ee, v2
	v_fmamk_f32 v155, v155, 0x3e0293ee, v2
	v_fmamk_f32 v156, v156, 0x3e0293ee, v2
	v_fmamk_f32 v157, v157, 0x3e0293ee, v2
	v_fmamk_f32 v158, v158, 0x3e0293ee, v2
	v_fmac_f32_e32 v2, 0x3e0293ee, v159
	v_exp_f32_e32 v159, v6
	v_exp_f32_e32 v163, v7
	v_exp_f32_e32 v165, v2
	v_add_f32_e32 v2, 0, v3
	v_exp_f32_e32 v8, v8
	v_add_f32_e32 v2, v4, v2
	v_exp_f32_e32 v9, v9
	v_add_f32_e32 v2, v5, v2
	v_exp_f32_e32 v10, v10
	v_add_f32_e32 v2, v159, v2
	v_exp_f32_e32 v11, v11
	v_add_f32_e32 v2, v163, v2
	v_exp_f32_e32 v12, v12
	v_add_f32_e32 v2, v8, v2
	v_exp_f32_e32 v13, v13
	v_add_f32_e32 v2, v9, v2
	v_exp_f32_e32 v164, v14
	v_add_f32_e32 v2, v10, v2
	v_exp_f32_e32 v15, v15
	v_add_f32_e32 v2, v11, v2
	v_exp_f32_e32 v160, v160
	v_add_f32_e32 v2, v12, v2
	v_exp_f32_e32 v161, v161
	v_add_f32_e32 v2, v13, v2
	v_exp_f32_e32 v162, v162
	v_add_f32_e32 v2, v164, v2
	v_exp_f32_e32 v144, v144
	v_add_f32_e32 v2, v15, v2
	v_exp_f32_e32 v145, v145
	v_add_f32_e32 v2, v160, v2
	v_exp_f32_e32 v146, v146
	v_add_f32_e32 v2, v161, v2
	v_exp_f32_e32 v147, v147
	v_add_f32_e32 v2, v162, v2
	v_exp_f32_e32 v148, v148
	v_add_f32_e32 v2, v144, v2
	v_exp_f32_e32 v149, v149
	v_add_f32_e32 v2, v145, v2
	v_exp_f32_e32 v150, v150
	v_add_f32_e32 v2, v146, v2
	v_exp_f32_e32 v151, v151
	v_add_f32_e32 v2, v147, v2
	v_exp_f32_e32 v152, v152
	v_add_f32_e32 v2, v148, v2
	v_exp_f32_e32 v153, v153
	v_add_f32_e32 v2, v149, v2
	v_exp_f32_e32 v154, v154
	v_add_f32_e32 v2, v150, v2
	v_exp_f32_e32 v155, v155
	v_add_f32_e32 v2, v151, v2
	v_exp_f32_e32 v156, v156
	v_add_f32_e32 v2, v152, v2
	v_exp_f32_e32 v157, v157
	v_add_f32_e32 v2, v153, v2
	v_exp_f32_e32 v158, v158
	v_add_f32_e32 v2, v154, v2
	v_add_f32_e32 v2, v155, v2
	v_add_f32_e32 v2, v156, v2
	v_add_f32_e32 v2, v157, v2
	v_add_f32_e32 v2, v158, v2
	v_add_f32_e32 v2, v165, v2
	v_mov_b32_e32 v6, v2
	s_nop 1
	v_permlane32_swap_b32_e32 v2, v6
	v_add_f32_e32 v14, v2, v6
	v_fma_f32 v250, v250, v0, v14
	v_cvt_pk_bf16_f32 v6, v3, v4
	v_cvt_pk_bf16_f32 v7, v5, v159
	v_cvt_pk_bf16_f32 v8, v163, v8
	v_cvt_pk_bf16_f32 v9, v9, v10
	v_cvt_pk_bf16_f32 v10, v11, v12
	v_cvt_pk_bf16_f32 v11, v13, v164
	v_cvt_pk_bf16_f32 v12, v15, v160
	v_cvt_pk_bf16_f32 v13, v161, v162
	v_cvt_pk_bf16_f32 v144, v144, v145
	v_cvt_pk_bf16_f32 v145, v146, v147
	v_cvt_pk_bf16_f32 v146, v148, v149
	v_cvt_pk_bf16_f32 v147, v150, v151
	v_cvt_pk_bf16_f32 v2, v152, v153
	v_cvt_pk_bf16_f32 v3, v154, v155
	v_cvt_pk_bf16_f32 v4, v156, v157
	v_cvt_pk_bf16_f32 v5, v158, v165
	s_nop 0
	v_permlane32_swap_b32_e32 v6, v8
	v_permlane32_swap_b32_e32 v7, v9
	v_permlane32_swap_b32_e32 v10, v12
	v_permlane32_swap_b32_e32 v11, v13
	v_permlane32_swap_b32_e32 v144, v146
	v_permlane32_swap_b32_e32 v145, v147
	v_permlane32_swap_b32_e32 v2, v4
	v_permlane32_swap_b32_e32 v3, v5
	ds_read_b64_tr_b16 v[148:149], v246 offset:0x8000
	ds_read_b64_tr_b16 v[150:151], v246 offset:0x8800
	ds_read_b64_tr_b16 v[152:153], v246 offset:0xc000
	ds_read_b64_tr_b16 v[154:155], v246 offset:0xc800
	ds_read_b64_tr_b16 v[156:157], v246 offset:0x9000
	ds_read_b64_tr_b16 v[158:159], v246 offset:0x9800
	ds_read_b64_tr_b16 v[160:161], v246 offset:0xd000
	ds_read_b64_tr_b16 v[162:163], v246 offset:0xd800
	ds_read_b64_tr_b16 v[164:165], v246 offset:0xa000
	ds_read_b64_tr_b16 v[166:167], v246 offset:0xa800
	ds_read_b64_tr_b16 v[168:169], v246 offset:0xe000
	ds_read_b64_tr_b16 v[170:171], v246 offset:0xe800
	ds_read_b64_tr_b16 v[172:173], v246 offset:0xb000
	ds_read_b64_tr_b16 v[174:175], v246 offset:0xb800
	ds_read_b64_tr_b16 v[176:177], v246 offset:0xf000
	ds_read_b64_tr_b16 v[178:179], v246 offset:0xf800
	s_waitcnt lgkmcnt(0)
; #define A3_BAR() do { asm volatile("s_waitcnt vmcnt(0) lgkmcnt(0)" ::: "memory"); __builtin_amdgcn_s_barrier(); asm volatile("" ::: "memory"); } while (0)
; __device__ __forceinline__ void pv_tile2(f32x16* o, f32x16* o2, int vb0, bf16x8 pa0, bf16x8 pa1, bf16x8 pa2, bf16x8 pa3) {
;     ...
;     PV2_D0(0); PV2_D0(1); PV2_D0(2); PV2_D0(3);
; __device__ __forceinline__ void attn_block3(const BlockRef& cur, char* lds, const int wid) {
;     ...
;         pv_tile2(o, o2, vbase + (t & 1) * 2 * SHM_V, pa0, pa1, pa2, pa3);
;         A3_BAR();
	s_nop 0
	v_mfma_f32_32x32x16_bf16 v[112:127], v[6:9], v[148:151], v[112:127]
	ds_read_b64_tr_b16 v[148:149], v246 offset:0x8200
	ds_read_b64_tr_b16 v[150:151], v246 offset:0x8a00
	v_mfma_f32_32x32x16_bf16 v[128:143], v[6:9], v[152:155], v[128:143]
	ds_read_b64_tr_b16 v[152:153], v246 offset:0xc200
	ds_read_b64_tr_b16 v[154:155], v246 offset:0xca00
	v_mfma_f32_32x32x16_bf16 v[112:127], v[10:13], v[156:159], v[112:127]
	ds_read_b64_tr_b16 v[156:157], v246 offset:0x9200
	ds_read_b64_tr_b16 v[158:159], v246 offset:0x9a00
	v_mfma_f32_32x32x16_bf16 v[128:143], v[10:13], v[160:163], v[128:143]
	ds_read_b64_tr_b16 v[160:161], v246 offset:0xd200
	ds_read_b64_tr_b16 v[162:163], v246 offset:0xda00
	v_mfma_f32_32x32x16_bf16 v[112:127], v[144:147], v[164:167], v[112:127]
	ds_read_b64_tr_b16 v[164:165], v246 offset:0xa200
	ds_read_b64_tr_b16 v[166:167], v246 offset:0xaa00
	v_mfma_f32_32x32x16_bf16 v[128:143], v[144:147], v[168:171], v[128:143]
	ds_read_b64_tr_b16 v[168:169], v246 offset:0xe200
	ds_read_b64_tr_b16 v[170:171], v246 offset:0xea00
	v_mfma_f32_32x32x16_bf16 v[112:127], v[2:5], v[172:175], v[112:127]
	ds_read_b64_tr_b16 v[172:173], v246 offset:0xb200
	ds_read_b64_tr_b16 v[174:175], v246 offset:0xba00
	v_mfma_f32_32x32x16_bf16 v[128:143], v[2:5], v[176:179], v[128:143]
	ds_read_b64_tr_b16 v[176:177], v246 offset:0xf200
	ds_read_b64_tr_b16 v[178:179], v246 offset:0xfa00
	s_waitcnt lgkmcnt(0)
	v_mfma_f32_32x32x16_bf16 v[80:95], v[6:9], v[148:151], v[80:95]
	ds_read_b64_tr_b16 v[148:149], v246 offset:0x8400
	ds_read_b64_tr_b16 v[150:151], v246 offset:0x8c00
	v_mfma_f32_32x32x16_bf16 v[96:111], v[6:9], v[152:155], v[96:111]
	ds_read_b64_tr_b16 v[152:153], v246 offset:0xc400
	ds_read_b64_tr_b16 v[154:155], v246 offset:0xcc00
	v_mfma_f32_32x32x16_bf16 v[80:95], v[10:13], v[156:159], v[80:95]
	ds_read_b64_tr_b16 v[156:157], v246 offset:0x9400
	ds_read_b64_tr_b16 v[158:159], v246 offset:0x9c00
	v_mfma_f32_32x32x16_bf16 v[96:111], v[10:13], v[160:163], v[96:111]
	ds_read_b64_tr_b16 v[160:161], v246 offset:0xd400
	ds_read_b64_tr_b16 v[162:163], v246 offset:0xdc00
	v_mfma_f32_32x32x16_bf16 v[80:95], v[144:147], v[164:167], v[80:95]
	ds_read_b64_tr_b16 v[164:165], v246 offset:0xa400
	ds_read_b64_tr_b16 v[166:167], v246 offset:0xac00
	v_mfma_f32_32x32x16_bf16 v[96:111], v[144:147], v[168:171], v[96:111]
	ds_read_b64_tr_b16 v[168:169], v246 offset:0xe400
	ds_read_b64_tr_b16 v[170:171], v246 offset:0xec00
	v_mfma_f32_32x32x16_bf16 v[80:95], v[2:5], v[172:175], v[80:95]
	ds_read_b64_tr_b16 v[172:173], v246 offset:0xb400
	ds_read_b64_tr_b16 v[174:175], v246 offset:0xbc00
	v_mfma_f32_32x32x16_bf16 v[96:111], v[2:5], v[176:179], v[96:111]
	ds_read_b64_tr_b16 v[176:177], v246 offset:0xf400
	ds_read_b64_tr_b16 v[178:179], v246 offset:0xfc00
	s_waitcnt lgkmcnt(0)
	v_mfma_f32_32x32x16_bf16 v[48:63], v[6:9], v[148:151], v[48:63]
	ds_read_b64_tr_b16 v[148:149], v246 offset:0x8600
	ds_read_b64_tr_b16 v[150:151], v246 offset:0x8e00
	v_mfma_f32_32x32x16_bf16 v[64:79], v[6:9], v[152:155], v[64:79]
	ds_read_b64_tr_b16 v[152:153], v246 offset:0xc600
	ds_read_b64_tr_b16 v[154:155], v246 offset:0xce00
	v_mfma_f32_32x32x16_bf16 v[48:63], v[10:13], v[156:159], v[48:63]
	ds_read_b64_tr_b16 v[156:157], v246 offset:0x9600
	ds_read_b64_tr_b16 v[158:159], v246 offset:0x9e00
	v_mfma_f32_32x32x16_bf16 v[64:79], v[10:13], v[160:163], v[64:79]
	ds_read_b64_tr_b16 v[160:161], v246 offset:0xd600
	ds_read_b64_tr_b16 v[162:163], v246 offset:0xde00
	v_mfma_f32_32x32x16_bf16 v[48:63], v[144:147], v[164:167], v[48:63]
	ds_read_b64_tr_b16 v[164:165], v246 offset:0xa600
	ds_read_b64_tr_b16 v[166:167], v246 offset:0xae00
	v_mfma_f32_32x32x16_bf16 v[64:79], v[144:147], v[168:171], v[64:79]
	ds_read_b64_tr_b16 v[168:169], v246 offset:0xe600
	ds_read_b64_tr_b16 v[170:171], v246 offset:0xee00
	v_mfma_f32_32x32x16_bf16 v[48:63], v[2:5], v[172:175], v[48:63]
	ds_read_b64_tr_b16 v[172:173], v246 offset:0xb600
	ds_read_b64_tr_b16 v[174:175], v246 offset:0xbe00
	v_mfma_f32_32x32x16_bf16 v[64:79], v[2:5], v[176:179], v[64:79]
	ds_read_b64_tr_b16 v[176:177], v246 offset:0xf600
	ds_read_b64_tr_b16 v[178:179], v246 offset:0xfe00
	s_waitcnt lgkmcnt(0)
	v_mfma_f32_32x32x16_bf16 v[16:31], v[6:9], v[148:151], v[16:31]
	s_add_u32 s68, s68, 0x4000
	s_addc_u32 s69, s69, 0
	s_add_u32 s98, s98, 0x4000
	s_addc_u32 s99, s99, 0
	s_add_u32 s100, s100, 0x4000
	s_addc_u32 s101, s101, 0
	s_add_i32 s90, s90, 64
	s_waitcnt vmcnt(0) lgkmcnt(0)
	s_barrier
	v_add_u32_e32 v247, 0xffffff00, v247
	v_mfma_f32_32x32x16_bf16 v[32:47], v[6:9], v[152:155], v[32:47]
	v_subrev_u32_e32 v248, 64, v248
	s_cmp_eq_u32 s88, s93
	v_mfma_f32_32x32x16_bf16 v[16:31], v[10:13], v[156:159], v[16:31]
	v_mfma_f32_32x32x16_bf16 v[32:47], v[10:13], v[160:163], v[32:47]
	v_mfma_f32_32x32x16_bf16 v[16:31], v[144:147], v[164:167], v[16:31]
	v_mfma_f32_32x32x16_bf16 v[32:47], v[144:147], v[168:171], v[32:47]
	v_mfma_f32_32x32x16_bf16 v[16:31], v[2:5], v[172:175], v[16:31]
	v_mfma_f32_32x32x16_bf16 v[32:47], v[2:5], v[176:179], v[32:47]
	s_cbranch_scc1 .LBB0_491
	s_branch .LBB0_449

; #define PG8_STAGE(bufoff, gbase, voff) do { _Pragma("unroll") for (int _i = 0; _i < 2; ++_i) \
;         __builtin_amdgcn_global_load_lds((const unsigned*)((const char*)(gbase) + (voff)[_i]), (LAS unsigned*)(lds + (bufoff) + ldsw + _i * 8192), 16, 0, 0); } while (0)
; #define PG8_LDA(dst, b, h) do { _Pragma("unroll") for (int m = 0; m < 4; ++m) _Pragma("unroll") for (int k = 0; k < 2; ++k) dst[m][k] = *(const LAS bf16x8*)(lds + PG8_SA(b, h) + aoff + m * 2048 + k * 1024); } while (0)
; #define PG8_LDB(dst, b, h) do { _Pragma("unroll") for (int n = 0; n < 2; ++n) _Pragma("unroll") for (int k = 0; k < 2; ++k) dst[n][k] = *(const LAS bf16x8*)(lds + PG8_SB(b, h) + boff + n * 2048 + k * 1024); } while (0)
; #define PG8_MMA(ai, bj, At, Bt) do { __builtin_amdgcn_s_setprio(1); _Pragma("unroll") for (int m = 0; m < 4; ++m) _Pragma("unroll") for (int n = 0; n < 2; ++n) _Pragma("unroll") for (int k = 0; k < 2; ++k) \
;         acc[ai][bj][m][n] = __builtin_amdgcn_mfma_f32_16x16x32_bf16(Bt[n][k], At[m][k], acc[ai][bj][m][n], 0, 0, 0); __builtin_amdgcn_s_setprio(0); } while (0)
; #define PG8_WAIT_V(n) asm volatile("s_waitcnt vmcnt(" #n ")" ::: "memory")
; #define PG8_WAIT_L(n) asm volatile("s_waitcnt lgkmcnt(" #n ")" ::: "memory")
; #define PG8_BAR __builtin_amdgcn_s_barrier()
; #define PG8_SCHED __builtin_amdgcn_sched_barrier(0)
; template <class Epi>
; __device__ __forceinline__ void gemm_phase(LAS unsigned char* lds, const Gemm g, const StaticOrder& S, const Epi& E, const int wid) {
;     ...
;             PG8_LDB(B0, 0, 0); PG8_LDB(B1, 0, 1); PG8_SCHED; PG8_LDA(At, 0, 0); PG8_STAGE(PG8_SA(1, 1), a1 + hstepA, voffA);
;             PG8_WAIT_V(8); PG8_WAIT_L(0); PG8_BAR; PG8_MMA(0, 0, At, B0); PG8_MMA(0, 1, At, B1); PG8_BAR; PG8_SCHED;
;             PG8_LDA(At, 0, 1); PG8_STAGE(PG8_SB(0, 0), b2, voffB); PG8_STAGE(PG8_SB(0, 1), b2 + hstepB, voffB); PG8_STAGE(PG8_SA(0, 0), a2, voffA);
;             PG8_WAIT_V(8); PG8_WAIT_L(0); PG8_BAR; PG8_MMA(1, 0, At, B0); PG8_MMA(1, 1, At, B1); PG8_BAR; PG8_SCHED;
;             PG8_LDB(B0, 1, 0); PG8_LDB(B1, 1, 1); PG8_SCHED; PG8_LDA(At, 1, 0); PG8_STAGE(PG8_SA(0, 1), a2 + hstepA, voffA);
;             PG8_WAIT_V(8); PG8_WAIT_L(0); PG8_BAR; PG8_MMA(0, 0, At, B0); PG8_MMA(0, 1, At, B1); PG8_BAR; PG8_SCHED;
.LBB0_1669:
	ds_read_b128 v[144:147], v157
	ds_read_b128 v[148:151], v157 offset:1024
	ds_read_b128 v[160:163], v157 offset:2048
	ds_read_b128 v[164:167], v157 offset:3072
	ds_read_b128 v[168:171], v158
	ds_read_b128 v[172:175], v158 offset:1024
	ds_read_b128 v[176:179], v158 offset:2048
	ds_read_b128 v[180:183], v158 offset:3072
	s_add_u32 s6, s46, 0x100
	s_addc_u32 s7, s47, 0
	s_cmp_eq_u32 s55, 12
	s_cselect_b32 s51, s43, s7
	s_cselect_b32 s50, s42, s6
	s_cselect_b32 s49, s11, s54
	s_cselect_b32 s48, s21, s53
	s_add_i32 m0, s0, 0xc000
	ds_read_b128 v[184:187], v159
	global_load_lds_dwordx4 v136, s[46:47]
	s_add_i32 m0, s0, 0xe000
	ds_read_b128 v[188:191], v159 offset:1024
	global_load_lds_dwordx4 v138, s[46:47]
	ds_read_b128 v[192:195], v159 offset:2048
	ds_read_b128 v[196:199], v159 offset:3072
	ds_read_b128 v[200:203], v159 offset:4096
	ds_read_b128 v[204:207], v159 offset:5120
	ds_read_b128 v[208:211], v159 offset:6144
	ds_read_b128 v[212:215], v159 offset:7168
	s_waitcnt vmcnt(8)
	s_waitcnt lgkmcnt(0)
	s_barrier
	s_setprio 1
	s_waitcnt lgkmcnt(0)
	v_mfma_f32_16x16x32_bf16 v[124:127], v[144:147], v[184:187], v[124:127]
	v_mfma_f32_16x16x32_bf16 v[120:123], v[160:163], v[184:187], v[120:123]
	v_mfma_f32_16x16x32_bf16 v[116:119], v[144:147], v[192:195], v[116:119]
	v_mfma_f32_16x16x32_bf16 v[112:115], v[160:163], v[192:195], v[112:115]
	v_mfma_f32_16x16x32_bf16 v[108:111], v[144:147], v[200:203], v[108:111]
	v_mfma_f32_16x16x32_bf16 v[104:107], v[160:163], v[200:203], v[104:107]
	v_mfma_f32_16x16x32_bf16 v[100:103], v[144:147], v[208:211], v[100:103]
	v_mfma_f32_16x16x32_bf16 v[96:99], v[160:163], v[208:211], v[96:99]
	v_mfma_f32_16x16x32_bf16 v[124:127], v[148:151], v[188:191], v[124:127]
	v_mfma_f32_16x16x32_bf16 v[120:123], v[164:167], v[188:191], v[120:123]
	v_mfma_f32_16x16x32_bf16 v[116:119], v[148:151], v[196:199], v[116:119]
	v_mfma_f32_16x16x32_bf16 v[112:115], v[164:167], v[196:199], v[112:115]
	v_mfma_f32_16x16x32_bf16 v[108:111], v[148:151], v[204:207], v[108:111]
	v_mfma_f32_16x16x32_bf16 v[104:107], v[164:167], v[204:207], v[104:107]
	v_mfma_f32_16x16x32_bf16 v[100:103], v[148:151], v[212:215], v[100:103]
	v_mfma_f32_16x16x32_bf16 v[96:99], v[164:167], v[212:215], v[96:99]
	s_setprio 0
	s_setprio 1
	v_mfma_f32_16x16x32_bf16 v[68:71], v[168:171], v[184:187], v[68:71]
	v_mfma_f32_16x16x32_bf16 v[60:63], v[176:179], v[184:187], v[60:63]
	v_mfma_f32_16x16x32_bf16 v[52:55], v[168:171], v[192:195], v[52:55]
	v_mfma_f32_16x16x32_bf16 v[48:51], v[176:179], v[192:195], v[48:51]
	v_mfma_f32_16x16x32_bf16 v[44:47], v[168:171], v[200:203], v[44:47]
	v_mfma_f32_16x16x32_bf16 v[40:43], v[176:179], v[200:203], v[40:43]
	v_mfma_f32_16x16x32_bf16 v[36:39], v[168:171], v[208:211], v[36:39]
	v_mfma_f32_16x16x32_bf16 v[32:35], v[176:179], v[208:211], v[32:35]
	v_mfma_f32_16x16x32_bf16 v[68:71], v[172:175], v[188:191], v[68:71]
	v_mfma_f32_16x16x32_bf16 v[60:63], v[180:183], v[188:191], v[60:63]
	v_mfma_f32_16x16x32_bf16 v[52:55], v[172:175], v[196:199], v[52:55]
	v_mfma_f32_16x16x32_bf16 v[48:51], v[180:183], v[196:199], v[48:51]
	v_mfma_f32_16x16x32_bf16 v[44:47], v[172:175], v[204:207], v[44:47]
	v_mfma_f32_16x16x32_bf16 v[40:43], v[180:183], v[204:207], v[40:43]
	v_mfma_f32_16x16x32_bf16 v[36:39], v[172:175], v[212:215], v[36:39]
	v_mfma_f32_16x16x32_bf16 v[32:35], v[180:183], v[212:215], v[32:35]
	s_setprio 0
	s_barrier
	s_add_i32 s24, s36, s94
	s_mov_b32 m0, s24
	ds_read_b128 v[184:187], v159 offset:16384
	global_load_lds_dwordx4 v132, s[48:49]
	s_add_i32 m0, s24, 0x2000
	s_add_u32 s24, s48, 0x40000
	s_addc_u32 s25, s49, 0
	s_add_i32 s46, s37, s94
	global_load_lds_dwordx4 v128, s[48:49]
	s_mov_b32 m0, s46
	ds_read_b128 v[188:191], v159 offset:17408
	global_load_lds_dwordx4 v132, s[24:25]
	s_add_i32 m0, s46, 0x2000
	ds_read_b128 v[192:195], v159 offset:18432
	global_load_lds_dwordx4 v128, s[24:25]
	s_mov_b32 m0, s0
	ds_read_b128 v[196:199], v159 offset:19456
	global_load_lds_dwordx4 v134, s[50:51]
	s_mov_b32 m0, s1
	ds_read_b128 v[200:203], v159 offset:20480
	global_load_lds_dwordx4 v130, s[50:51]
	ds_read_b128 v[204:207], v159 offset:21504
	ds_read_b128 v[208:211], v159 offset:22528
	ds_read_b128 v[212:215], v159 offset:23552
	s_waitcnt vmcnt(8)
	s_waitcnt lgkmcnt(0)
	s_barrier
	s_setprio 1
	s_waitcnt lgkmcnt(0)
	v_mfma_f32_16x16x32_bf16 v[92:95], v[144:147], v[184:187], v[92:95]
	v_mfma_f32_16x16x32_bf16 v[88:91], v[160:163], v[184:187], v[88:91]
	v_mfma_f32_16x16x32_bf16 v[84:87], v[144:147], v[192:195], v[84:87]
	v_mfma_f32_16x16x32_bf16 v[80:83], v[160:163], v[192:195], v[80:83]
	v_mfma_f32_16x16x32_bf16 v[76:79], v[144:147], v[200:203], v[76:79]
	v_mfma_f32_16x16x32_bf16 v[72:75], v[160:163], v[200:203], v[72:75]
	v_mfma_f32_16x16x32_bf16 v[64:67], v[144:147], v[208:211], v[64:67]
	v_mfma_f32_16x16x32_bf16 v[56:59], v[160:163], v[208:211], v[56:59]
	v_mfma_f32_16x16x32_bf16 v[92:95], v[148:151], v[188:191], v[92:95]
	v_mfma_f32_16x16x32_bf16 v[88:91], v[164:167], v[188:191], v[88:91]
	v_mfma_f32_16x16x32_bf16 v[84:87], v[148:151], v[196:199], v[84:87]
	v_mfma_f32_16x16x32_bf16 v[80:83], v[164:167], v[196:199], v[80:83]
	v_mfma_f32_16x16x32_bf16 v[76:79], v[148:151], v[204:207], v[76:79]
	v_mfma_f32_16x16x32_bf16 v[72:75], v[164:167], v[204:207], v[72:75]
	v_mfma_f32_16x16x32_bf16 v[64:67], v[148:151], v[212:215], v[64:67]
	v_mfma_f32_16x16x32_bf16 v[56:59], v[164:167], v[212:215], v[56:59]
	s_setprio 0
	s_setprio 1
	v_mfma_f32_16x16x32_bf16 v[28:31], v[168:171], v[184:187], v[28:31]
	v_mfma_f32_16x16x32_bf16 v[24:27], v[176:179], v[184:187], v[24:27]
	v_mfma_f32_16x16x32_bf16 v[20:23], v[168:171], v[192:195], v[20:23]
	v_mfma_f32_16x16x32_bf16 v[16:19], v[176:179], v[192:195], v[16:19]
	v_mfma_f32_16x16x32_bf16 v[12:15], v[168:171], v[200:203], v[12:15]
	v_mfma_f32_16x16x32_bf16 v[8:11], v[176:179], v[200:203], v[8:11]
	v_mfma_f32_16x16x32_bf16 v[4:7], v[168:171], v[208:211], v[4:7]
	v_mfma_f32_16x16x32_bf16 v[0:3], v[176:179], v[208:211], v[0:3]
	v_mfma_f32_16x16x32_bf16 v[28:31], v[172:175], v[188:191], v[28:31]
	v_mfma_f32_16x16x32_bf16 v[24:27], v[180:183], v[188:191], v[24:27]
	v_mfma_f32_16x16x32_bf16 v[20:23], v[172:175], v[196:199], v[20:23]
	v_mfma_f32_16x16x32_bf16 v[16:19], v[180:183], v[196:199], v[16:19]
	v_mfma_f32_16x16x32_bf16 v[12:15], v[172:175], v[204:207], v[12:15]
	v_mfma_f32_16x16x32_bf16 v[8:11], v[180:183], v[204:207], v[8:11]
	v_mfma_f32_16x16x32_bf16 v[4:7], v[172:175], v[212:215], v[4:7]
	v_mfma_f32_16x16x32_bf16 v[0:3], v[180:183], v[212:215], v[0:3]
	s_setprio 0
	s_barrier
; #define PG8_STAGE(bufoff, gbase, voff) do { _Pragma("unroll") for (int _i = 0; _i < 2; ++_i) \
;         __builtin_amdgcn_global_load_lds((const unsigned*)((const char*)(gbase) + (voff)[_i]), (LAS unsigned*)(lds + (bufoff) + ldsw + _i * 8192), 16, 0, 0); } while (0)
; #define PG8_LDA(dst, b, h) do { _Pragma("unroll") for (int m = 0; m < 4; ++m) _Pragma("unroll") for (int k = 0; k < 2; ++k) dst[m][k] = *(const LAS bf16x8*)(lds + PG8_SA(b, h) + aoff + m * 2048 + k * 1024); } while (0)
; #define PG8_LDB(dst, b, h) do { _Pragma("unroll") for (int n = 0; n < 2; ++n) _Pragma("unroll") for (int k = 0; k < 2; ++k) dst[n][k] = *(const LAS bf16x8*)(lds + PG8_SB(b, h) + boff + n * 2048 + k * 1024); } while (0)
; #define PG8_MMA(ai, bj, At, Bt) do { __builtin_amdgcn_s_setprio(1); _Pragma("unroll") for (int m = 0; m < 4; ++m) _Pragma("unroll") for (int n = 0; n < 2; ++n) _Pragma("unroll") for (int k = 0; k < 2; ++k) \
;         acc[ai][bj][m][n] = __builtin_amdgcn_mfma_f32_16x16x32_bf16(Bt[n][k], At[m][k], acc[ai][bj][m][n], 0, 0, 0); __builtin_amdgcn_s_setprio(0); } while (0)
; #define PG8_WAIT_V(n) asm volatile("s_waitcnt vmcnt(" #n ")" ::: "memory")
; #define PG8_WAIT_L(n) asm volatile("s_waitcnt lgkmcnt(" #n ")" ::: "memory")
; #define PG8_BAR __builtin_amdgcn_s_barrier()
; #define PG8_SCHED __builtin_amdgcn_sched_barrier(0)
; template <class Epi>
; __device__ __forceinline__ void gemm_phase(LAS unsigned char* lds, const Gemm g, const StaticOrder& S, const Epi& E, const int wid) {
;     ...
;             PG8_LDB(B0, 1, 0); PG8_LDB(B1, 1, 1); PG8_SCHED; PG8_LDA(At, 1, 0); PG8_STAGE(PG8_SA(0, 1), a2 + hstepA, voffA);
;             PG8_WAIT_V(8); PG8_WAIT_L(0); PG8_BAR; PG8_MMA(0, 0, At, B0); PG8_MMA(0, 1, At, B1); PG8_BAR; PG8_SCHED;
;             PG8_LDA(At, 1, 1); PG8_STAGE(PG8_SB(1, 0), b3, voffB); PG8_STAGE(PG8_SB(1, 1), b3 + hstepB, voffB); PG8_STAGE(PG8_SA(1, 0), a3, voffA);
;             PG8_WAIT_V(8); PG8_WAIT_L(0); PG8_BAR; PG8_MMA(1, 0, At, B0); PG8_MMA(1, 1, At, B1); PG8_BAR; PG8_SCHED;
;         }
	s_add_i32 s46, 0, 0x18000
	s_add_i32 s47, 0, 0x1c000
	v_add_u32_e32 v164, s46, v154
	v_add_u32_e32 v180, s47, v154
	ds_read_b128 v[144:147], v164
	ds_read_b128 v[148:151], v164 offset:1024
	ds_read_b128 v[160:163], v164 offset:2048
	ds_read_b128 v[164:167], v164 offset:3072
	ds_read_b128 v[168:171], v180
	ds_read_b128 v[172:175], v180 offset:1024
	ds_read_b128 v[176:179], v180 offset:2048
	ds_read_b128 v[180:183], v180 offset:3072
	s_add_u32 s24, s50, 0x40000
	s_addc_u32 s25, s51, 0
	s_mov_b32 m0, s15
	ds_read_b128 v[184:187], v159 offset:32768
	global_load_lds_dwordx4 v134, s[24:25]
	s_mov_b32 m0, s26
	ds_read_b128 v[188:191], v159 offset:33792
	global_load_lds_dwordx4 v130, s[24:25]
	ds_read_b128 v[192:195], v159 offset:34816
	ds_read_b128 v[196:199], v159 offset:35840
	ds_read_b128 v[200:203], v159 offset:36864
	ds_read_b128 v[204:207], v159 offset:37888
	ds_read_b128 v[208:211], v159 offset:38912
	ds_read_b128 v[212:215], v159 offset:39936
	s_waitcnt vmcnt(8)
	s_waitcnt lgkmcnt(0)
	s_barrier
	s_setprio 1
	s_waitcnt lgkmcnt(0)
	v_mfma_f32_16x16x32_bf16 v[124:127], v[144:147], v[184:187], v[124:127]
	v_mfma_f32_16x16x32_bf16 v[120:123], v[160:163], v[184:187], v[120:123]
	v_mfma_f32_16x16x32_bf16 v[116:119], v[144:147], v[192:195], v[116:119]
	v_mfma_f32_16x16x32_bf16 v[112:115], v[160:163], v[192:195], v[112:115]
	v_mfma_f32_16x16x32_bf16 v[108:111], v[144:147], v[200:203], v[108:111]
	v_mfma_f32_16x16x32_bf16 v[104:107], v[160:163], v[200:203], v[104:107]
	v_mfma_f32_16x16x32_bf16 v[100:103], v[144:147], v[208:211], v[100:103]
	v_mfma_f32_16x16x32_bf16 v[96:99], v[160:163], v[208:211], v[96:99]
	v_mfma_f32_16x16x32_bf16 v[124:127], v[148:151], v[188:191], v[124:127]
	v_mfma_f32_16x16x32_bf16 v[120:123], v[164:167], v[188:191], v[120:123]
	v_mfma_f32_16x16x32_bf16 v[116:119], v[148:151], v[196:199], v[116:119]
	v_mfma_f32_16x16x32_bf16 v[112:115], v[164:167], v[196:199], v[112:115]
	v_mfma_f32_16x16x32_bf16 v[108:111], v[148:151], v[204:207], v[108:111]
	v_mfma_f32_16x16x32_bf16 v[104:107], v[164:167], v[204:207], v[104:107]
	v_mfma_f32_16x16x32_bf16 v[100:103], v[148:151], v[212:215], v[100:103]
	v_mfma_f32_16x16x32_bf16 v[96:99], v[164:167], v[212:215], v[96:99]
	s_setprio 0
	s_setprio 1
	v_mfma_f32_16x16x32_bf16 v[68:71], v[168:171], v[184:187], v[68:71]
	v_mfma_f32_16x16x32_bf16 v[60:63], v[176:179], v[184:187], v[60:63]
	v_mfma_f32_16x16x32_bf16 v[52:55], v[168:171], v[192:195], v[52:55]
	v_mfma_f32_16x16x32_bf16 v[48:51], v[176:179], v[192:195], v[48:51]
	v_mfma_f32_16x16x32_bf16 v[44:47], v[168:171], v[200:203], v[44:47]
	v_mfma_f32_16x16x32_bf16 v[40:43], v[176:179], v[200:203], v[40:43]
	v_mfma_f32_16x16x32_bf16 v[36:39], v[168:171], v[208:211], v[36:39]
	v_mfma_f32_16x16x32_bf16 v[32:35], v[176:179], v[208:211], v[32:35]
	v_mfma_f32_16x16x32_bf16 v[68:71], v[172:175], v[188:191], v[68:71]
	v_mfma_f32_16x16x32_bf16 v[60:63], v[180:183], v[188:191], v[60:63]
	v_mfma_f32_16x16x32_bf16 v[52:55], v[172:175], v[196:199], v[52:55]
	v_mfma_f32_16x16x32_bf16 v[48:51], v[180:183], v[196:199], v[48:51]
	v_mfma_f32_16x16x32_bf16 v[44:47], v[172:175], v[204:207], v[44:47]
	v_mfma_f32_16x16x32_bf16 v[40:43], v[180:183], v[204:207], v[40:43]
	v_mfma_f32_16x16x32_bf16 v[36:39], v[172:175], v[212:215], v[36:39]
	v_mfma_f32_16x16x32_bf16 v[32:35], v[180:183], v[212:215], v[32:35]
	s_setprio 0
	s_barrier
	s_add_i32 s24, s46, s94
	s_add_u32 s98, s48, 0x80
	s_addc_u32 s99, s49, 0
	s_mov_b32 m0, s24
	ds_read_b128 v[184:187], v159 offset:49152
	global_load_lds_dwordx4 v132, s[98:99]
	s_add_i32 m0, s24, 0x2000
	s_add_u32 s24, s48, 0x40080
	s_addc_u32 s25, s49, 0
	s_add_i32 s46, s47, s94
	global_load_lds_dwordx4 v128, s[98:99]
	s_mov_b32 m0, s46
	ds_read_b128 v[188:191], v159 offset:50176
	global_load_lds_dwordx4 v132, s[24:25]
	s_add_i32 m0, s46, 0x2000
	ds_read_b128 v[192:195], v159 offset:51200
	global_load_lds_dwordx4 v128, s[24:25]
	s_add_u32 s100, s50, 0x80
	s_addc_u32 s101, s51, 0
	s_mov_b32 m0, s28
	ds_read_b128 v[196:199], v159 offset:52224
	global_load_lds_dwordx4 v134, s[100:101]
	s_mov_b32 m0, s29
	ds_read_b128 v[200:203], v159 offset:53248
	global_load_lds_dwordx4 v130, s[100:101]
	ds_read_b128 v[204:207], v159 offset:54272
	ds_read_b128 v[208:211], v159 offset:55296
	ds_read_b128 v[212:215], v159 offset:56320
	s_waitcnt vmcnt(8)
	s_waitcnt lgkmcnt(0)
	s_barrier
	s_setprio 1
	s_waitcnt lgkmcnt(0)
	v_mfma_f32_16x16x32_bf16 v[92:95], v[144:147], v[184:187], v[92:95]
	v_mfma_f32_16x16x32_bf16 v[88:91], v[160:163], v[184:187], v[88:91]
	v_mfma_f32_16x16x32_bf16 v[84:87], v[144:147], v[192:195], v[84:87]
	v_mfma_f32_16x16x32_bf16 v[80:83], v[160:163], v[192:195], v[80:83]
	v_mfma_f32_16x16x32_bf16 v[76:79], v[144:147], v[200:203], v[76:79]
	v_mfma_f32_16x16x32_bf16 v[72:75], v[160:163], v[200:203], v[72:75]
	v_mfma_f32_16x16x32_bf16 v[64:67], v[144:147], v[208:211], v[64:67]
	v_mfma_f32_16x16x32_bf16 v[56:59], v[160:163], v[208:211], v[56:59]
	v_mfma_f32_16x16x32_bf16 v[92:95], v[148:151], v[188:191], v[92:95]
	v_mfma_f32_16x16x32_bf16 v[88:91], v[164:167], v[188:191], v[88:91]
	v_mfma_f32_16x16x32_bf16 v[84:87], v[148:151], v[196:199], v[84:87]
	v_mfma_f32_16x16x32_bf16 v[80:83], v[164:167], v[196:199], v[80:83]
	v_mfma_f32_16x16x32_bf16 v[76:79], v[148:151], v[204:207], v[76:79]
	v_mfma_f32_16x16x32_bf16 v[72:75], v[164:167], v[204:207], v[72:75]
	v_mfma_f32_16x16x32_bf16 v[64:67], v[148:151], v[212:215], v[64:67]
	v_mfma_f32_16x16x32_bf16 v[56:59], v[164:167], v[212:215], v[56:59]
	s_setprio 0
	s_setprio 1
	v_mfma_f32_16x16x32_bf16 v[28:31], v[168:171], v[184:187], v[28:31]
	v_mfma_f32_16x16x32_bf16 v[24:27], v[176:179], v[184:187], v[24:27]
	v_mfma_f32_16x16x32_bf16 v[20:23], v[168:171], v[192:195], v[20:23]
	v_mfma_f32_16x16x32_bf16 v[16:19], v[176:179], v[192:195], v[16:19]
	v_mfma_f32_16x16x32_bf16 v[12:15], v[168:171], v[200:203], v[12:15]
	v_mfma_f32_16x16x32_bf16 v[8:11], v[176:179], v[200:203], v[8:11]
	v_mfma_f32_16x16x32_bf16 v[4:7], v[168:171], v[208:211], v[4:7]
	v_mfma_f32_16x16x32_bf16 v[0:3], v[176:179], v[208:211], v[0:3]
	v_mfma_f32_16x16x32_bf16 v[28:31], v[172:175], v[188:191], v[28:31]
	v_mfma_f32_16x16x32_bf16 v[24:27], v[180:183], v[188:191], v[24:27]
	v_mfma_f32_16x16x32_bf16 v[20:23], v[172:175], v[196:199], v[20:23]
	v_mfma_f32_16x16x32_bf16 v[16:19], v[180:183], v[196:199], v[16:19]
	v_mfma_f32_16x16x32_bf16 v[12:15], v[172:175], v[204:207], v[12:15]
	v_mfma_f32_16x16x32_bf16 v[8:11], v[180:183], v[204:207], v[8:11]
	v_mfma_f32_16x16x32_bf16 v[4:7], v[172:175], v[212:215], v[4:7]
	v_mfma_f32_16x16x32_bf16 v[0:3], v[180:183], v[212:215], v[0:3]
	s_setprio 0
	s_add_i32 s55, s55, 2
	s_add_u32 s53, s53, 0x100
	s_addc_u32 s54, s54, 0
	s_cmp_gt_u32 s55, 13
	s_mov_b64 s[46:47], s[6:7]
	s_barrier
	s_cbranch_scc0 .LBB0_1669
	s_and_b64 vcc, exec, s[22:23]
	s_cbranch_vccz .LBB0_1672
	s_barrier

; #define PG8_STAGE(bufoff, gbase, voff) do { _Pragma("unroll") for (int _i = 0; _i < 2; ++_i) \
;         __builtin_amdgcn_global_load_lds((const unsigned*)((const char*)(gbase) + (voff)[_i]), (LAS unsigned*)(lds + (bufoff) + ldsw + _i * 8192), 16, 0, 0); } while (0)
; #define PG8_LDA(dst, b, h) do { _Pragma("unroll") for (int m = 0; m < 4; ++m) _Pragma("unroll") for (int k = 0; k < 2; ++k) dst[m][k] = *(const LAS bf16x8*)(lds + PG8_SA(b, h) + aoff + m * 2048 + k * 1024); } while (0)
; #define PG8_LDB(dst, b, h) do { _Pragma("unroll") for (int n = 0; n < 2; ++n) _Pragma("unroll") for (int k = 0; k < 2; ++k) dst[n][k] = *(const LAS bf16x8*)(lds + PG8_SB(b, h) + boff + n * 2048 + k * 1024); } while (0)
; #define PG8_MMA(ai, bj, At, Bt) do { __builtin_amdgcn_s_setprio(1); _Pragma("unroll") for (int m = 0; m < 4; ++m) _Pragma("unroll") for (int n = 0; n < 2; ++n) _Pragma("unroll") for (int k = 0; k < 2; ++k) \
;         acc[ai][bj][m][n] = __builtin_amdgcn_mfma_f32_16x16x32_bf16(Bt[n][k], At[m][k], acc[ai][bj][m][n], 0, 0, 0); __builtin_amdgcn_s_setprio(0); } while (0)
; #define PG8_WAIT_V(n) asm volatile("s_waitcnt vmcnt(" #n ")" ::: "memory")
; #define PG8_WAIT_L(n) asm volatile("s_waitcnt lgkmcnt(" #n ")" ::: "memory")
; #define PG8_BAR __builtin_amdgcn_s_barrier()
; #define PG8_SCHED __builtin_amdgcn_sched_barrier(0)
; template <class Epi>
; __device__ __forceinline__ void gemm_phase(LAS unsigned char* lds, const Gemm g, const StaticOrder& S, const Epi& E, const int wid) {
;     ...
;             PG8_LDB(B0, 0, 0); PG8_LDB(B1, 0, 1); PG8_SCHED; PG8_LDA(At, 0, 0); PG8_STAGE(PG8_SA(1, 1), a1 + hstepA, voffA);
;             PG8_WAIT_V(8); PG8_WAIT_L(0); PG8_BAR; PG8_MMA(0, 0, At, B0); PG8_MMA(0, 1, At, B1); PG8_BAR; PG8_SCHED;
;             PG8_LDA(At, 0, 1); PG8_STAGE(PG8_SB(0, 0), b2, voffB); PG8_STAGE(PG8_SB(0, 1), b2 + hstepB, voffB); PG8_STAGE(PG8_SA(0, 0), a2, voffA);
;             PG8_WAIT_V(8); PG8_WAIT_L(0); PG8_BAR; PG8_MMA(1, 0, At, B0); PG8_MMA(1, 1, At, B1); PG8_BAR; PG8_SCHED;
;             PG8_LDB(B0, 1, 0); PG8_LDB(B1, 1, 1); PG8_SCHED; PG8_LDA(At, 1, 0); PG8_STAGE(PG8_SA(0, 1), a2 + hstepA, voffA);
;             PG8_WAIT_V(8); PG8_WAIT_L(0); PG8_BAR; PG8_MMA(0, 0, At, B0); PG8_MMA(0, 1, At, B1); PG8_BAR; PG8_SCHED;
.LBB0_1692:
	ds_read_b128 v[144:147], v159
	ds_read_b128 v[148:151], v159 offset:1024
	ds_read_b128 v[152:155], v159 offset:2048
	ds_read_b128 v[162:165], v159 offset:3072
	ds_read_b128 v[166:169], v160
	ds_read_b128 v[170:173], v160 offset:1024
	ds_read_b128 v[174:177], v160 offset:2048
	ds_read_b128 v[178:181], v160 offset:3072
	s_add_u32 s6, s50, 0x100
	s_addc_u32 s7, s51, 0
	s_cmp_eq_u32 s58, 12
	s_cselect_b32 s55, s47, s7
	s_cselect_b32 s54, s46, s6
	s_cselect_b32 s53, s21, s57
	s_cselect_b32 s52, s38, s45
	s_add_i32 m0, s0, 0xc000
	ds_read_b128 v[182:185], v161
	global_load_lds_dwordx4 v136, s[50:51]
	s_add_i32 m0, s0, 0xe000
	ds_read_b128 v[186:189], v161 offset:1024
	global_load_lds_dwordx4 v138, s[50:51]
	ds_read_b128 v[190:193], v161 offset:2048
	ds_read_b128 v[194:197], v161 offset:3072
	ds_read_b128 v[198:201], v161 offset:4096
	ds_read_b128 v[202:205], v161 offset:5120
	ds_read_b128 v[206:209], v161 offset:6144
	ds_read_b128 v[210:213], v161 offset:7168
	s_waitcnt vmcnt(8)
	s_waitcnt lgkmcnt(0)
	s_barrier
	s_setprio 1
	s_waitcnt lgkmcnt(0)
	v_mfma_f32_16x16x32_bf16 v[124:127], v[144:147], v[182:185], v[124:127]
	v_mfma_f32_16x16x32_bf16 v[120:123], v[152:155], v[182:185], v[120:123]
	v_mfma_f32_16x16x32_bf16 v[116:119], v[144:147], v[190:193], v[116:119]
	v_mfma_f32_16x16x32_bf16 v[112:115], v[152:155], v[190:193], v[112:115]
	v_mfma_f32_16x16x32_bf16 v[108:111], v[144:147], v[198:201], v[108:111]
	v_mfma_f32_16x16x32_bf16 v[104:107], v[152:155], v[198:201], v[104:107]
	v_mfma_f32_16x16x32_bf16 v[100:103], v[144:147], v[206:209], v[100:103]
	v_mfma_f32_16x16x32_bf16 v[96:99], v[152:155], v[206:209], v[96:99]
	v_mfma_f32_16x16x32_bf16 v[124:127], v[148:151], v[186:189], v[124:127]
	v_mfma_f32_16x16x32_bf16 v[120:123], v[162:165], v[186:189], v[120:123]
	v_mfma_f32_16x16x32_bf16 v[116:119], v[148:151], v[194:197], v[116:119]
	v_mfma_f32_16x16x32_bf16 v[112:115], v[162:165], v[194:197], v[112:115]
	v_mfma_f32_16x16x32_bf16 v[108:111], v[148:151], v[202:205], v[108:111]
	v_mfma_f32_16x16x32_bf16 v[104:107], v[162:165], v[202:205], v[104:107]
	v_mfma_f32_16x16x32_bf16 v[100:103], v[148:151], v[210:213], v[100:103]
	v_mfma_f32_16x16x32_bf16 v[96:99], v[162:165], v[210:213], v[96:99]
	s_setprio 0
	s_setprio 1
	v_mfma_f32_16x16x32_bf16 v[60:63], v[166:169], v[182:185], v[60:63]
	v_mfma_f32_16x16x32_bf16 v[56:59], v[174:177], v[182:185], v[56:59]
	v_mfma_f32_16x16x32_bf16 v[52:55], v[166:169], v[190:193], v[52:55]
	v_mfma_f32_16x16x32_bf16 v[48:51], v[174:177], v[190:193], v[48:51]
	v_mfma_f32_16x16x32_bf16 v[44:47], v[166:169], v[198:201], v[44:47]
	v_mfma_f32_16x16x32_bf16 v[40:43], v[174:177], v[198:201], v[40:43]
	v_mfma_f32_16x16x32_bf16 v[36:39], v[166:169], v[206:209], v[36:39]
	v_mfma_f32_16x16x32_bf16 v[32:35], v[174:177], v[206:209], v[32:35]
	v_mfma_f32_16x16x32_bf16 v[60:63], v[170:173], v[186:189], v[60:63]
	v_mfma_f32_16x16x32_bf16 v[56:59], v[178:181], v[186:189], v[56:59]
	v_mfma_f32_16x16x32_bf16 v[52:55], v[170:173], v[194:197], v[52:55]
	v_mfma_f32_16x16x32_bf16 v[48:51], v[178:181], v[194:197], v[48:51]
	v_mfma_f32_16x16x32_bf16 v[44:47], v[170:173], v[202:205], v[44:47]
	v_mfma_f32_16x16x32_bf16 v[40:43], v[178:181], v[202:205], v[40:43]
	v_mfma_f32_16x16x32_bf16 v[36:39], v[170:173], v[210:213], v[36:39]
	v_mfma_f32_16x16x32_bf16 v[32:35], v[178:181], v[210:213], v[32:35]
	s_setprio 0
	s_barrier
	s_add_i32 s24, s34, s94
	s_mov_b32 m0, s24
	ds_read_b128 v[182:185], v161 offset:16384
	global_load_lds_dwordx4 v132, s[52:53]
	s_add_i32 m0, s24, 0x2000
	s_add_u32 s24, s52, 0x40000
	s_addc_u32 s25, s53, 0
	s_add_i32 s50, s35, s94
	global_load_lds_dwordx4 v128, s[52:53]
	s_mov_b32 m0, s50
	ds_read_b128 v[186:189], v161 offset:17408
	global_load_lds_dwordx4 v132, s[24:25]
	s_add_i32 m0, s50, 0x2000
	ds_read_b128 v[190:193], v161 offset:18432
	global_load_lds_dwordx4 v128, s[24:25]
	s_mov_b32 m0, s0
	ds_read_b128 v[194:197], v161 offset:19456
	global_load_lds_dwordx4 v134, s[54:55]
	s_mov_b32 m0, s1
	ds_read_b128 v[198:201], v161 offset:20480
	global_load_lds_dwordx4 v130, s[54:55]
	ds_read_b128 v[202:205], v161 offset:21504
	ds_read_b128 v[206:209], v161 offset:22528
	ds_read_b128 v[210:213], v161 offset:23552
	s_waitcnt vmcnt(8)
	s_waitcnt lgkmcnt(0)
	s_barrier
	s_setprio 1
	s_waitcnt lgkmcnt(0)
	v_mfma_f32_16x16x32_bf16 v[92:95], v[144:147], v[182:185], v[92:95]
	v_mfma_f32_16x16x32_bf16 v[88:91], v[152:155], v[182:185], v[88:91]
	v_mfma_f32_16x16x32_bf16 v[84:87], v[144:147], v[190:193], v[84:87]
	v_mfma_f32_16x16x32_bf16 v[80:83], v[152:155], v[190:193], v[80:83]
	v_mfma_f32_16x16x32_bf16 v[76:79], v[144:147], v[198:201], v[76:79]
	v_mfma_f32_16x16x32_bf16 v[72:75], v[152:155], v[198:201], v[72:75]
	v_mfma_f32_16x16x32_bf16 v[68:71], v[144:147], v[206:209], v[68:71]
	v_mfma_f32_16x16x32_bf16 v[64:67], v[152:155], v[206:209], v[64:67]
	v_mfma_f32_16x16x32_bf16 v[92:95], v[148:151], v[186:189], v[92:95]
	v_mfma_f32_16x16x32_bf16 v[88:91], v[162:165], v[186:189], v[88:91]
	v_mfma_f32_16x16x32_bf16 v[84:87], v[148:151], v[194:197], v[84:87]
	v_mfma_f32_16x16x32_bf16 v[80:83], v[162:165], v[194:197], v[80:83]
	v_mfma_f32_16x16x32_bf16 v[76:79], v[148:151], v[202:205], v[76:79]
	v_mfma_f32_16x16x32_bf16 v[72:75], v[162:165], v[202:205], v[72:75]
	v_mfma_f32_16x16x32_bf16 v[68:71], v[148:151], v[210:213], v[68:71]
	v_mfma_f32_16x16x32_bf16 v[64:67], v[162:165], v[210:213], v[64:67]
	s_setprio 0
	s_setprio 1
	v_mfma_f32_16x16x32_bf16 v[28:31], v[166:169], v[182:185], v[28:31]
	v_mfma_f32_16x16x32_bf16 v[24:27], v[174:177], v[182:185], v[24:27]
	v_mfma_f32_16x16x32_bf16 v[20:23], v[166:169], v[190:193], v[20:23]
	v_mfma_f32_16x16x32_bf16 v[16:19], v[174:177], v[190:193], v[16:19]
	v_mfma_f32_16x16x32_bf16 v[12:15], v[166:169], v[198:201], v[12:15]
	v_mfma_f32_16x16x32_bf16 v[8:11], v[174:177], v[198:201], v[8:11]
	v_mfma_f32_16x16x32_bf16 v[4:7], v[166:169], v[206:209], v[4:7]
	v_mfma_f32_16x16x32_bf16 v[0:3], v[174:177], v[206:209], v[0:3]
	v_mfma_f32_16x16x32_bf16 v[28:31], v[170:173], v[186:189], v[28:31]
	v_mfma_f32_16x16x32_bf16 v[24:27], v[178:181], v[186:189], v[24:27]
	v_mfma_f32_16x16x32_bf16 v[20:23], v[170:173], v[194:197], v[20:23]
	v_mfma_f32_16x16x32_bf16 v[16:19], v[178:181], v[194:197], v[16:19]
	v_mfma_f32_16x16x32_bf16 v[12:15], v[170:173], v[202:205], v[12:15]
	v_mfma_f32_16x16x32_bf16 v[8:11], v[178:181], v[202:205], v[8:11]
	v_mfma_f32_16x16x32_bf16 v[4:7], v[170:173], v[210:213], v[4:7]
	v_mfma_f32_16x16x32_bf16 v[0:3], v[178:181], v[210:213], v[0:3]
	s_setprio 0
	s_barrier
; #define PG8_STAGE(bufoff, gbase, voff) do { _Pragma("unroll") for (int _i = 0; _i < 2; ++_i) \
;         __builtin_amdgcn_global_load_lds((const unsigned*)((const char*)(gbase) + (voff)[_i]), (LAS unsigned*)(lds + (bufoff) + ldsw + _i * 8192), 16, 0, 0); } while (0)
; #define PG8_LDA(dst, b, h) do { _Pragma("unroll") for (int m = 0; m < 4; ++m) _Pragma("unroll") for (int k = 0; k < 2; ++k) dst[m][k] = *(const LAS bf16x8*)(lds + PG8_SA(b, h) + aoff + m * 2048 + k * 1024); } while (0)
; #define PG8_LDB(dst, b, h) do { _Pragma("unroll") for (int n = 0; n < 2; ++n) _Pragma("unroll") for (int k = 0; k < 2; ++k) dst[n][k] = *(const LAS bf16x8*)(lds + PG8_SB(b, h) + boff + n * 2048 + k * 1024); } while (0)
; #define PG8_MMA(ai, bj, At, Bt) do { __builtin_amdgcn_s_setprio(1); _Pragma("unroll") for (int m = 0; m < 4; ++m) _Pragma("unroll") for (int n = 0; n < 2; ++n) _Pragma("unroll") for (int k = 0; k < 2; ++k) \
;         acc[ai][bj][m][n] = __builtin_amdgcn_mfma_f32_16x16x32_bf16(Bt[n][k], At[m][k], acc[ai][bj][m][n], 0, 0, 0); __builtin_amdgcn_s_setprio(0); } while (0)
; #define PG8_WAIT_V(n) asm volatile("s_waitcnt vmcnt(" #n ")" ::: "memory")
; #define PG8_WAIT_L(n) asm volatile("s_waitcnt lgkmcnt(" #n ")" ::: "memory")
; #define PG8_BAR __builtin_amdgcn_s_barrier()
; #define PG8_SCHED __builtin_amdgcn_sched_barrier(0)
; template <class Epi>
; __device__ __forceinline__ void gemm_phase(LAS unsigned char* lds, const Gemm g, const StaticOrder& S, const Epi& E, const int wid) {
;     ...
;             PG8_LDB(B0, 1, 0); PG8_LDB(B1, 1, 1); PG8_SCHED; PG8_LDA(At, 1, 0); PG8_STAGE(PG8_SA(0, 1), a2 + hstepA, voffA);
;             PG8_WAIT_V(8); PG8_WAIT_L(0); PG8_BAR; PG8_MMA(0, 0, At, B0); PG8_MMA(0, 1, At, B1); PG8_BAR; PG8_SCHED;
;             PG8_LDA(At, 1, 1); PG8_STAGE(PG8_SB(1, 0), b3, voffB); PG8_STAGE(PG8_SB(1, 1), b3 + hstepB, voffB); PG8_STAGE(PG8_SA(1, 0), a3, voffA);
;             PG8_WAIT_V(8); PG8_WAIT_L(0); PG8_BAR; PG8_MMA(1, 0, At, B0); PG8_MMA(1, 1, At, B1); PG8_BAR; PG8_SCHED;
;         }
	s_add_i32 s50, 0, 0x18000
	s_add_i32 s51, 0, 0x1c000
	v_add_u32_e32 v162, s50, v156
	v_add_u32_e32 v178, s51, v156
	ds_read_b128 v[144:147], v162
	ds_read_b128 v[148:151], v162 offset:1024
	ds_read_b128 v[152:155], v162 offset:2048
	ds_read_b128 v[162:165], v162 offset:3072
	ds_read_b128 v[166:169], v178
	ds_read_b128 v[170:173], v178 offset:1024
	ds_read_b128 v[174:177], v178 offset:2048
	ds_read_b128 v[178:181], v178 offset:3072
	s_add_u32 s24, s54, 0x40000
	s_addc_u32 s25, s55, 0
	s_mov_b32 m0, s15
	ds_read_b128 v[182:185], v161 offset:32768
	global_load_lds_dwordx4 v134, s[24:25]
	s_mov_b32 m0, s26
	ds_read_b128 v[186:189], v161 offset:33792
	global_load_lds_dwordx4 v130, s[24:25]
	ds_read_b128 v[190:193], v161 offset:34816
	ds_read_b128 v[194:197], v161 offset:35840
	ds_read_b128 v[198:201], v161 offset:36864
	ds_read_b128 v[202:205], v161 offset:37888
	ds_read_b128 v[206:209], v161 offset:38912
	ds_read_b128 v[210:213], v161 offset:39936
	s_waitcnt vmcnt(8)
	s_waitcnt lgkmcnt(0)
	s_barrier
	s_setprio 1
	s_waitcnt lgkmcnt(0)
	v_mfma_f32_16x16x32_bf16 v[124:127], v[144:147], v[182:185], v[124:127]
	v_mfma_f32_16x16x32_bf16 v[120:123], v[152:155], v[182:185], v[120:123]
	v_mfma_f32_16x16x32_bf16 v[116:119], v[144:147], v[190:193], v[116:119]
	v_mfma_f32_16x16x32_bf16 v[112:115], v[152:155], v[190:193], v[112:115]
	v_mfma_f32_16x16x32_bf16 v[108:111], v[144:147], v[198:201], v[108:111]
	v_mfma_f32_16x16x32_bf16 v[104:107], v[152:155], v[198:201], v[104:107]
	v_mfma_f32_16x16x32_bf16 v[100:103], v[144:147], v[206:209], v[100:103]
	v_mfma_f32_16x16x32_bf16 v[96:99], v[152:155], v[206:209], v[96:99]
	v_mfma_f32_16x16x32_bf16 v[124:127], v[148:151], v[186:189], v[124:127]
	v_mfma_f32_16x16x32_bf16 v[120:123], v[162:165], v[186:189], v[120:123]
	v_mfma_f32_16x16x32_bf16 v[116:119], v[148:151], v[194:197], v[116:119]
	v_mfma_f32_16x16x32_bf16 v[112:115], v[162:165], v[194:197], v[112:115]
	v_mfma_f32_16x16x32_bf16 v[108:111], v[148:151], v[202:205], v[108:111]
	v_mfma_f32_16x16x32_bf16 v[104:107], v[162:165], v[202:205], v[104:107]
	v_mfma_f32_16x16x32_bf16 v[100:103], v[148:151], v[210:213], v[100:103]
	v_mfma_f32_16x16x32_bf16 v[96:99], v[162:165], v[210:213], v[96:99]
	s_setprio 0
	s_setprio 1
	v_mfma_f32_16x16x32_bf16 v[60:63], v[166:169], v[182:185], v[60:63]
	v_mfma_f32_16x16x32_bf16 v[56:59], v[174:177], v[182:185], v[56:59]
	v_mfma_f32_16x16x32_bf16 v[52:55], v[166:169], v[190:193], v[52:55]
	v_mfma_f32_16x16x32_bf16 v[48:51], v[174:177], v[190:193], v[48:51]
	v_mfma_f32_16x16x32_bf16 v[44:47], v[166:169], v[198:201], v[44:47]
	v_mfma_f32_16x16x32_bf16 v[40:43], v[174:177], v[198:201], v[40:43]
	v_mfma_f32_16x16x32_bf16 v[36:39], v[166:169], v[206:209], v[36:39]
	v_mfma_f32_16x16x32_bf16 v[32:35], v[174:177], v[206:209], v[32:35]
	v_mfma_f32_16x16x32_bf16 v[60:63], v[170:173], v[186:189], v[60:63]
	v_mfma_f32_16x16x32_bf16 v[56:59], v[178:181], v[186:189], v[56:59]
	v_mfma_f32_16x16x32_bf16 v[52:55], v[170:173], v[194:197], v[52:55]
	v_mfma_f32_16x16x32_bf16 v[48:51], v[178:181], v[194:197], v[48:51]
	v_mfma_f32_16x16x32_bf16 v[44:47], v[170:173], v[202:205], v[44:47]
	v_mfma_f32_16x16x32_bf16 v[40:43], v[178:181], v[202:205], v[40:43]
	v_mfma_f32_16x16x32_bf16 v[36:39], v[170:173], v[210:213], v[36:39]
	v_mfma_f32_16x16x32_bf16 v[32:35], v[178:181], v[210:213], v[32:35]
	s_setprio 0
	s_barrier
	s_add_i32 s24, s50, s94
	s_add_u32 s98, s52, 0x80
	s_addc_u32 s99, s53, 0
	s_mov_b32 m0, s24
	ds_read_b128 v[182:185], v161 offset:49152
	global_load_lds_dwordx4 v132, s[98:99]
	s_add_i32 m0, s24, 0x2000
	s_add_u32 s24, s52, 0x40080
	s_addc_u32 s25, s53, 0
	s_add_i32 s50, s51, s94
	global_load_lds_dwordx4 v128, s[98:99]
	s_mov_b32 m0, s50
	ds_read_b128 v[186:189], v161 offset:50176
	global_load_lds_dwordx4 v132, s[24:25]
	s_add_i32 m0, s50, 0x2000
	ds_read_b128 v[190:193], v161 offset:51200
	global_load_lds_dwordx4 v128, s[24:25]
	s_add_u32 s100, s54, 0x80
	s_addc_u32 s101, s55, 0
	s_mov_b32 m0, s28
	ds_read_b128 v[194:197], v161 offset:52224
	global_load_lds_dwordx4 v134, s[100:101]
	s_mov_b32 m0, s29
	ds_read_b128 v[198:201], v161 offset:53248
	global_load_lds_dwordx4 v130, s[100:101]
	ds_read_b128 v[202:205], v161 offset:54272
	ds_read_b128 v[206:209], v161 offset:55296
	ds_read_b128 v[210:213], v161 offset:56320
	s_waitcnt vmcnt(8)
	s_waitcnt lgkmcnt(0)
	s_barrier
	s_setprio 1
	s_waitcnt lgkmcnt(0)
	v_mfma_f32_16x16x32_bf16 v[92:95], v[144:147], v[182:185], v[92:95]
	v_mfma_f32_16x16x32_bf16 v[88:91], v[152:155], v[182:185], v[88:91]
	v_mfma_f32_16x16x32_bf16 v[84:87], v[144:147], v[190:193], v[84:87]
	v_mfma_f32_16x16x32_bf16 v[80:83], v[152:155], v[190:193], v[80:83]
	v_mfma_f32_16x16x32_bf16 v[76:79], v[144:147], v[198:201], v[76:79]
	v_mfma_f32_16x16x32_bf16 v[72:75], v[152:155], v[198:201], v[72:75]
	v_mfma_f32_16x16x32_bf16 v[68:71], v[144:147], v[206:209], v[68:71]
	v_mfma_f32_16x16x32_bf16 v[64:67], v[152:155], v[206:209], v[64:67]
	v_mfma_f32_16x16x32_bf16 v[92:95], v[148:151], v[186:189], v[92:95]
	v_mfma_f32_16x16x32_bf16 v[88:91], v[162:165], v[186:189], v[88:91]
	v_mfma_f32_16x16x32_bf16 v[84:87], v[148:151], v[194:197], v[84:87]
	v_mfma_f32_16x16x32_bf16 v[80:83], v[162:165], v[194:197], v[80:83]
	v_mfma_f32_16x16x32_bf16 v[76:79], v[148:151], v[202:205], v[76:79]
	v_mfma_f32_16x16x32_bf16 v[72:75], v[162:165], v[202:205], v[72:75]
	v_mfma_f32_16x16x32_bf16 v[68:71], v[148:151], v[210:213], v[68:71]
	v_mfma_f32_16x16x32_bf16 v[64:67], v[162:165], v[210:213], v[64:67]
	s_setprio 0
	s_setprio 1
	v_mfma_f32_16x16x32_bf16 v[28:31], v[166:169], v[182:185], v[28:31]
	v_mfma_f32_16x16x32_bf16 v[24:27], v[174:177], v[182:185], v[24:27]
	v_mfma_f32_16x16x32_bf16 v[20:23], v[166:169], v[190:193], v[20:23]
	v_mfma_f32_16x16x32_bf16 v[16:19], v[174:177], v[190:193], v[16:19]
	v_mfma_f32_16x16x32_bf16 v[12:15], v[166:169], v[198:201], v[12:15]
	v_mfma_f32_16x16x32_bf16 v[8:11], v[174:177], v[198:201], v[8:11]
	v_mfma_f32_16x16x32_bf16 v[4:7], v[166:169], v[206:209], v[4:7]
	v_mfma_f32_16x16x32_bf16 v[0:3], v[174:177], v[206:209], v[0:3]
	v_mfma_f32_16x16x32_bf16 v[28:31], v[170:173], v[186:189], v[28:31]
	v_mfma_f32_16x16x32_bf16 v[24:27], v[178:181], v[186:189], v[24:27]
	v_mfma_f32_16x16x32_bf16 v[20:23], v[170:173], v[194:197], v[20:23]
	v_mfma_f32_16x16x32_bf16 v[16:19], v[178:181], v[194:197], v[16:19]
	v_mfma_f32_16x16x32_bf16 v[12:15], v[170:173], v[202:205], v[12:15]
	v_mfma_f32_16x16x32_bf16 v[8:11], v[178:181], v[202:205], v[8:11]
	v_mfma_f32_16x16x32_bf16 v[4:7], v[170:173], v[210:213], v[4:7]
	v_mfma_f32_16x16x32_bf16 v[0:3], v[178:181], v[210:213], v[0:3]
	s_setprio 0
	s_add_i32 s58, s58, 2
	s_add_u32 s45, s45, 0x100
	s_addc_u32 s57, s57, 0
	s_cmp_gt_u32 s58, 13
	s_mov_b64 s[50:51], s[6:7]
	s_barrier
	s_cbranch_scc0 .LBB0_1692
	s_and_b64 vcc, exec, s[22:23]
	s_cbranch_vccz .LBB0_1695
	s_barrier

; #define PG8_STAGE(bufoff, gbase, voff) do { _Pragma("unroll") for (int _i = 0; _i < 2; ++_i) \
;         __builtin_amdgcn_global_load_lds((const unsigned*)((const char*)(gbase) + (voff)[_i]), (LAS unsigned*)(lds + (bufoff) + ldsw + _i * 8192), 16, 0, 0); } while (0)
; #define PG8_LDA(dst, b, h) do { _Pragma("unroll") for (int m = 0; m < 4; ++m) _Pragma("unroll") for (int k = 0; k < 2; ++k) dst[m][k] = *(const LAS bf16x8*)(lds + PG8_SA(b, h) + aoff + m * 2048 + k * 1024); } while (0)
; #define PG8_LDB(dst, b, h) do { _Pragma("unroll") for (int n = 0; n < 2; ++n) _Pragma("unroll") for (int k = 0; k < 2; ++k) dst[n][k] = *(const LAS bf16x8*)(lds + PG8_SB(b, h) + boff + n * 2048 + k * 1024); } while (0)
; #define PG8_MMA(ai, bj, At, Bt) do { __builtin_amdgcn_s_setprio(1); _Pragma("unroll") for (int m = 0; m < 4; ++m) _Pragma("unroll") for (int n = 0; n < 2; ++n) _Pragma("unroll") for (int k = 0; k < 2; ++k) \
;         acc[ai][bj][m][n] = __builtin_amdgcn_mfma_f32_16x16x32_bf16(Bt[n][k], At[m][k], acc[ai][bj][m][n], 0, 0, 0); __builtin_amdgcn_s_setprio(0); } while (0)
; #define PG8_WAIT_V(n) asm volatile("s_waitcnt vmcnt(" #n ")" ::: "memory")
; #define PG8_WAIT_L(n) asm volatile("s_waitcnt lgkmcnt(" #n ")" ::: "memory")
; #define PG8_BAR __builtin_amdgcn_s_barrier()
; #define PG8_SCHED __builtin_amdgcn_sched_barrier(0)
; template <class Epi>
; __device__ __forceinline__ void gemm_phase(LAS unsigned char* lds, const Gemm g, const StaticOrder& S, const Epi& E, const int wid) {
;     ...
;             PG8_LDB(B0, 0, 0); PG8_LDB(B1, 0, 1); PG8_SCHED; PG8_LDA(At, 0, 0); PG8_STAGE(PG8_SA(1, 1), a1 + hstepA, voffA);
;             PG8_WAIT_V(8); PG8_WAIT_L(0); PG8_BAR; PG8_MMA(0, 0, At, B0); PG8_MMA(0, 1, At, B1); PG8_BAR; PG8_SCHED;
;             PG8_LDA(At, 0, 1); PG8_STAGE(PG8_SB(0, 0), b2, voffB); PG8_STAGE(PG8_SB(0, 1), b2 + hstepB, voffB); PG8_STAGE(PG8_SA(0, 0), a2, voffA);
;             PG8_WAIT_V(8); PG8_WAIT_L(0); PG8_BAR; PG8_MMA(1, 0, At, B0); PG8_MMA(1, 1, At, B1); PG8_BAR; PG8_SCHED;
;             PG8_LDB(B0, 1, 0); PG8_LDB(B1, 1, 1); PG8_SCHED; PG8_LDA(At, 1, 0); PG8_STAGE(PG8_SA(0, 1), a2 + hstepA, voffA);
;             PG8_WAIT_V(8); PG8_WAIT_L(0); PG8_BAR; PG8_MMA(0, 0, At, B0); PG8_MMA(0, 1, At, B1); PG8_BAR; PG8_SCHED;
.LBB0_1727:
	ds_read_b128 v[144:147], v157
	ds_read_b128 v[148:151], v157 offset:1024
	ds_read_b128 v[160:163], v157 offset:2048
	ds_read_b128 v[164:167], v157 offset:3072
	ds_read_b128 v[168:171], v158
	ds_read_b128 v[172:175], v158 offset:1024
	ds_read_b128 v[176:179], v158 offset:2048
	ds_read_b128 v[180:183], v158 offset:3072
	s_add_u32 s6, s46, 0x100
	s_addc_u32 s7, s47, 0
	s_cmp_eq_u32 s54, 28
	s_cselect_b32 s51, s43, s7
	s_cselect_b32 s50, s42, s6
	s_cselect_b32 s49, s21, s53
	s_cselect_b32 s48, s41, s52
	s_add_i32 m0, s1, 0xc000
	ds_read_b128 v[184:187], v159
	global_load_lds_dwordx4 v136, s[46:47]
	s_add_i32 m0, s1, 0xe000
	ds_read_b128 v[188:191], v159 offset:1024
	global_load_lds_dwordx4 v138, s[46:47]
	ds_read_b128 v[192:195], v159 offset:2048
	ds_read_b128 v[196:199], v159 offset:3072
	ds_read_b128 v[200:203], v159 offset:4096
	ds_read_b128 v[204:207], v159 offset:5120
	ds_read_b128 v[208:211], v159 offset:6144
	ds_read_b128 v[212:215], v159 offset:7168
	s_waitcnt vmcnt(8)
	s_waitcnt lgkmcnt(0)
	s_barrier
	s_setprio 1
	s_waitcnt lgkmcnt(0)
	v_mfma_f32_16x16x32_bf16 v[124:127], v[144:147], v[184:187], v[124:127]
	v_mfma_f32_16x16x32_bf16 v[120:123], v[160:163], v[184:187], v[120:123]
	v_mfma_f32_16x16x32_bf16 v[116:119], v[144:147], v[192:195], v[116:119]
	v_mfma_f32_16x16x32_bf16 v[112:115], v[160:163], v[192:195], v[112:115]
	v_mfma_f32_16x16x32_bf16 v[108:111], v[144:147], v[200:203], v[108:111]
	v_mfma_f32_16x16x32_bf16 v[104:107], v[160:163], v[200:203], v[104:107]
	v_mfma_f32_16x16x32_bf16 v[100:103], v[144:147], v[208:211], v[100:103]
	v_mfma_f32_16x16x32_bf16 v[96:99], v[160:163], v[208:211], v[96:99]
	v_mfma_f32_16x16x32_bf16 v[124:127], v[148:151], v[188:191], v[124:127]
	v_mfma_f32_16x16x32_bf16 v[120:123], v[164:167], v[188:191], v[120:123]
	v_mfma_f32_16x16x32_bf16 v[116:119], v[148:151], v[196:199], v[116:119]
	v_mfma_f32_16x16x32_bf16 v[112:115], v[164:167], v[196:199], v[112:115]
	v_mfma_f32_16x16x32_bf16 v[108:111], v[148:151], v[204:207], v[108:111]
	v_mfma_f32_16x16x32_bf16 v[104:107], v[164:167], v[204:207], v[104:107]
	v_mfma_f32_16x16x32_bf16 v[100:103], v[148:151], v[212:215], v[100:103]
	v_mfma_f32_16x16x32_bf16 v[96:99], v[164:167], v[212:215], v[96:99]
	s_setprio 0
	s_setprio 1
	v_mfma_f32_16x16x32_bf16 v[76:79], v[168:171], v[184:187], v[76:79]
	v_mfma_f32_16x16x32_bf16 v[64:67], v[176:179], v[184:187], v[64:67]
	v_mfma_f32_16x16x32_bf16 v[56:59], v[168:171], v[192:195], v[56:59]
	v_mfma_f32_16x16x32_bf16 v[48:51], v[176:179], v[192:195], v[48:51]
	v_mfma_f32_16x16x32_bf16 v[44:47], v[168:171], v[200:203], v[44:47]
	v_mfma_f32_16x16x32_bf16 v[40:43], v[176:179], v[200:203], v[40:43]
	v_mfma_f32_16x16x32_bf16 v[36:39], v[168:171], v[208:211], v[36:39]
	v_mfma_f32_16x16x32_bf16 v[32:35], v[176:179], v[208:211], v[32:35]
	v_mfma_f32_16x16x32_bf16 v[76:79], v[172:175], v[188:191], v[76:79]
	v_mfma_f32_16x16x32_bf16 v[64:67], v[180:183], v[188:191], v[64:67]
	v_mfma_f32_16x16x32_bf16 v[56:59], v[172:175], v[196:199], v[56:59]
	v_mfma_f32_16x16x32_bf16 v[48:51], v[180:183], v[196:199], v[48:51]
	v_mfma_f32_16x16x32_bf16 v[44:47], v[172:175], v[204:207], v[44:47]
	v_mfma_f32_16x16x32_bf16 v[40:43], v[180:183], v[204:207], v[40:43]
	v_mfma_f32_16x16x32_bf16 v[36:39], v[172:175], v[212:215], v[36:39]
	v_mfma_f32_16x16x32_bf16 v[32:35], v[180:183], v[212:215], v[32:35]
	s_setprio 0
	s_barrier
	s_add_i32 s24, s35, s94
	s_mov_b32 m0, s24
	ds_read_b128 v[184:187], v159 offset:16384
	global_load_lds_dwordx4 v132, s[48:49]
	s_add_i32 m0, s24, 0x2000
	s_add_u32 s24, s48, 0x80000
	s_addc_u32 s25, s49, 0
	s_add_i32 s46, s36, s94
	global_load_lds_dwordx4 v128, s[48:49]
	s_mov_b32 m0, s46
	ds_read_b128 v[188:191], v159 offset:17408
	global_load_lds_dwordx4 v132, s[24:25]
	s_add_i32 m0, s46, 0x2000
	ds_read_b128 v[192:195], v159 offset:18432
	global_load_lds_dwordx4 v128, s[24:25]
	s_mov_b32 m0, s1
	ds_read_b128 v[196:199], v159 offset:19456
	global_load_lds_dwordx4 v134, s[50:51]
	s_mov_b32 m0, s15
	ds_read_b128 v[200:203], v159 offset:20480
	global_load_lds_dwordx4 v130, s[50:51]
	ds_read_b128 v[204:207], v159 offset:21504
	ds_read_b128 v[208:211], v159 offset:22528
	ds_read_b128 v[212:215], v159 offset:23552
	s_waitcnt vmcnt(8)
	s_waitcnt lgkmcnt(0)
	s_barrier
	s_setprio 1
	s_waitcnt lgkmcnt(0)
	v_mfma_f32_16x16x32_bf16 v[92:95], v[144:147], v[184:187], v[92:95]
	v_mfma_f32_16x16x32_bf16 v[88:91], v[160:163], v[184:187], v[88:91]
	v_mfma_f32_16x16x32_bf16 v[84:87], v[144:147], v[192:195], v[84:87]
	v_mfma_f32_16x16x32_bf16 v[80:83], v[160:163], v[192:195], v[80:83]
	v_mfma_f32_16x16x32_bf16 v[72:75], v[144:147], v[200:203], v[72:75]
	v_mfma_f32_16x16x32_bf16 v[68:71], v[160:163], v[200:203], v[68:71]
	v_mfma_f32_16x16x32_bf16 v[60:63], v[144:147], v[208:211], v[60:63]
	v_mfma_f32_16x16x32_bf16 v[52:55], v[160:163], v[208:211], v[52:55]
	v_mfma_f32_16x16x32_bf16 v[92:95], v[148:151], v[188:191], v[92:95]
	v_mfma_f32_16x16x32_bf16 v[88:91], v[164:167], v[188:191], v[88:91]
	v_mfma_f32_16x16x32_bf16 v[84:87], v[148:151], v[196:199], v[84:87]
	v_mfma_f32_16x16x32_bf16 v[80:83], v[164:167], v[196:199], v[80:83]
	v_mfma_f32_16x16x32_bf16 v[72:75], v[148:151], v[204:207], v[72:75]
	v_mfma_f32_16x16x32_bf16 v[68:71], v[164:167], v[204:207], v[68:71]
	v_mfma_f32_16x16x32_bf16 v[60:63], v[148:151], v[212:215], v[60:63]
	v_mfma_f32_16x16x32_bf16 v[52:55], v[164:167], v[212:215], v[52:55]
	s_setprio 0
	s_setprio 1
	v_mfma_f32_16x16x32_bf16 v[28:31], v[168:171], v[184:187], v[28:31]
	v_mfma_f32_16x16x32_bf16 v[24:27], v[176:179], v[184:187], v[24:27]
	v_mfma_f32_16x16x32_bf16 v[20:23], v[168:171], v[192:195], v[20:23]
	v_mfma_f32_16x16x32_bf16 v[16:19], v[176:179], v[192:195], v[16:19]
	v_mfma_f32_16x16x32_bf16 v[12:15], v[168:171], v[200:203], v[12:15]
	v_mfma_f32_16x16x32_bf16 v[8:11], v[176:179], v[200:203], v[8:11]
	v_mfma_f32_16x16x32_bf16 v[4:7], v[168:171], v[208:211], v[4:7]
	v_mfma_f32_16x16x32_bf16 v[0:3], v[176:179], v[208:211], v[0:3]
	v_mfma_f32_16x16x32_bf16 v[28:31], v[172:175], v[188:191], v[28:31]
	v_mfma_f32_16x16x32_bf16 v[24:27], v[180:183], v[188:191], v[24:27]
	v_mfma_f32_16x16x32_bf16 v[20:23], v[172:175], v[196:199], v[20:23]
	v_mfma_f32_16x16x32_bf16 v[16:19], v[180:183], v[196:199], v[16:19]
	v_mfma_f32_16x16x32_bf16 v[12:15], v[172:175], v[204:207], v[12:15]
	v_mfma_f32_16x16x32_bf16 v[8:11], v[180:183], v[204:207], v[8:11]
	v_mfma_f32_16x16x32_bf16 v[4:7], v[172:175], v[212:215], v[4:7]
	v_mfma_f32_16x16x32_bf16 v[0:3], v[180:183], v[212:215], v[0:3]
	s_setprio 0
	s_barrier
; #define PG8_STAGE(bufoff, gbase, voff) do { _Pragma("unroll") for (int _i = 0; _i < 2; ++_i) \
;         __builtin_amdgcn_global_load_lds((const unsigned*)((const char*)(gbase) + (voff)[_i]), (LAS unsigned*)(lds + (bufoff) + ldsw + _i * 8192), 16, 0, 0); } while (0)
; #define PG8_LDA(dst, b, h) do { _Pragma("unroll") for (int m = 0; m < 4; ++m) _Pragma("unroll") for (int k = 0; k < 2; ++k) dst[m][k] = *(const LAS bf16x8*)(lds + PG8_SA(b, h) + aoff + m * 2048 + k * 1024); } while (0)
; #define PG8_LDB(dst, b, h) do { _Pragma("unroll") for (int n = 0; n < 2; ++n) _Pragma("unroll") for (int k = 0; k < 2; ++k) dst[n][k] = *(const LAS bf16x8*)(lds + PG8_SB(b, h) + boff + n * 2048 + k * 1024); } while (0)
; #define PG8_MMA(ai, bj, At, Bt) do { __builtin_amdgcn_s_setprio(1); _Pragma("unroll") for (int m = 0; m < 4; ++m) _Pragma("unroll") for (int n = 0; n < 2; ++n) _Pragma("unroll") for (int k = 0; k < 2; ++k) \
;         acc[ai][bj][m][n] = __builtin_amdgcn_mfma_f32_16x16x32_bf16(Bt[n][k], At[m][k], acc[ai][bj][m][n], 0, 0, 0); __builtin_amdgcn_s_setprio(0); } while (0)
; #define PG8_WAIT_V(n) asm volatile("s_waitcnt vmcnt(" #n ")" ::: "memory")
; #define PG8_WAIT_L(n) asm volatile("s_waitcnt lgkmcnt(" #n ")" ::: "memory")
; #define PG8_BAR __builtin_amdgcn_s_barrier()
; #define PG8_SCHED __builtin_amdgcn_sched_barrier(0)
; template <class Epi>
; __device__ __forceinline__ void gemm_phase(LAS unsigned char* lds, const Gemm g, const StaticOrder& S, const Epi& E, const int wid) {
;     ...
;             PG8_LDB(B0, 1, 0); PG8_LDB(B1, 1, 1); PG8_SCHED; PG8_LDA(At, 1, 0); PG8_STAGE(PG8_SA(0, 1), a2 + hstepA, voffA);
;             PG8_WAIT_V(8); PG8_WAIT_L(0); PG8_BAR; PG8_MMA(0, 0, At, B0); PG8_MMA(0, 1, At, B1); PG8_BAR; PG8_SCHED;
;             PG8_LDA(At, 1, 1); PG8_STAGE(PG8_SB(1, 0), b3, voffB); PG8_STAGE(PG8_SB(1, 1), b3 + hstepB, voffB); PG8_STAGE(PG8_SA(1, 0), a3, voffA);
;             PG8_WAIT_V(8); PG8_WAIT_L(0); PG8_BAR; PG8_MMA(1, 0, At, B0); PG8_MMA(1, 1, At, B1); PG8_BAR; PG8_SCHED;
;         }
	s_add_i32 s46, 0, 0x18000
	s_add_i32 s47, 0, 0x1c000
	v_add_u32_e32 v164, s46, v154
	v_add_u32_e32 v180, s47, v154
	ds_read_b128 v[144:147], v164
	ds_read_b128 v[148:151], v164 offset:1024
	ds_read_b128 v[160:163], v164 offset:2048
	ds_read_b128 v[164:167], v164 offset:3072
	ds_read_b128 v[168:171], v180
	ds_read_b128 v[172:175], v180 offset:1024
	ds_read_b128 v[176:179], v180 offset:2048
	ds_read_b128 v[180:183], v180 offset:3072
	s_add_u32 s24, s50, 0x80000
	s_addc_u32 s25, s51, 0
	s_mov_b32 m0, s26
	ds_read_b128 v[184:187], v159 offset:32768
	global_load_lds_dwordx4 v134, s[24:25]
	s_mov_b32 m0, s27
	ds_read_b128 v[188:191], v159 offset:33792
	global_load_lds_dwordx4 v130, s[24:25]
	ds_read_b128 v[192:195], v159 offset:34816
	ds_read_b128 v[196:199], v159 offset:35840
	ds_read_b128 v[200:203], v159 offset:36864
	ds_read_b128 v[204:207], v159 offset:37888
	ds_read_b128 v[208:211], v159 offset:38912
	ds_read_b128 v[212:215], v159 offset:39936
	s_waitcnt vmcnt(8)
	s_waitcnt lgkmcnt(0)
	s_barrier
	s_setprio 1
	s_waitcnt lgkmcnt(0)
	v_mfma_f32_16x16x32_bf16 v[124:127], v[144:147], v[184:187], v[124:127]
	v_mfma_f32_16x16x32_bf16 v[120:123], v[160:163], v[184:187], v[120:123]
	v_mfma_f32_16x16x32_bf16 v[116:119], v[144:147], v[192:195], v[116:119]
	v_mfma_f32_16x16x32_bf16 v[112:115], v[160:163], v[192:195], v[112:115]
	v_mfma_f32_16x16x32_bf16 v[108:111], v[144:147], v[200:203], v[108:111]
	v_mfma_f32_16x16x32_bf16 v[104:107], v[160:163], v[200:203], v[104:107]
	v_mfma_f32_16x16x32_bf16 v[100:103], v[144:147], v[208:211], v[100:103]
	v_mfma_f32_16x16x32_bf16 v[96:99], v[160:163], v[208:211], v[96:99]
	v_mfma_f32_16x16x32_bf16 v[124:127], v[148:151], v[188:191], v[124:127]
	v_mfma_f32_16x16x32_bf16 v[120:123], v[164:167], v[188:191], v[120:123]
	v_mfma_f32_16x16x32_bf16 v[116:119], v[148:151], v[196:199], v[116:119]
	v_mfma_f32_16x16x32_bf16 v[112:115], v[164:167], v[196:199], v[112:115]
	v_mfma_f32_16x16x32_bf16 v[108:111], v[148:151], v[204:207], v[108:111]
	v_mfma_f32_16x16x32_bf16 v[104:107], v[164:167], v[204:207], v[104:107]
	v_mfma_f32_16x16x32_bf16 v[100:103], v[148:151], v[212:215], v[100:103]
	v_mfma_f32_16x16x32_bf16 v[96:99], v[164:167], v[212:215], v[96:99]
	s_setprio 0
	s_setprio 1
	v_mfma_f32_16x16x32_bf16 v[76:79], v[168:171], v[184:187], v[76:79]
	v_mfma_f32_16x16x32_bf16 v[64:67], v[176:179], v[184:187], v[64:67]
	v_mfma_f32_16x16x32_bf16 v[56:59], v[168:171], v[192:195], v[56:59]
	v_mfma_f32_16x16x32_bf16 v[48:51], v[176:179], v[192:195], v[48:51]
	v_mfma_f32_16x16x32_bf16 v[44:47], v[168:171], v[200:203], v[44:47]
	v_mfma_f32_16x16x32_bf16 v[40:43], v[176:179], v[200:203], v[40:43]
	v_mfma_f32_16x16x32_bf16 v[36:39], v[168:171], v[208:211], v[36:39]
	v_mfma_f32_16x16x32_bf16 v[32:35], v[176:179], v[208:211], v[32:35]
	v_mfma_f32_16x16x32_bf16 v[76:79], v[172:175], v[188:191], v[76:79]
	v_mfma_f32_16x16x32_bf16 v[64:67], v[180:183], v[188:191], v[64:67]
	v_mfma_f32_16x16x32_bf16 v[56:59], v[172:175], v[196:199], v[56:59]
	v_mfma_f32_16x16x32_bf16 v[48:51], v[180:183], v[196:199], v[48:51]
	v_mfma_f32_16x16x32_bf16 v[44:47], v[172:175], v[204:207], v[44:47]
	v_mfma_f32_16x16x32_bf16 v[40:43], v[180:183], v[204:207], v[40:43]
	v_mfma_f32_16x16x32_bf16 v[36:39], v[172:175], v[212:215], v[36:39]
	v_mfma_f32_16x16x32_bf16 v[32:35], v[180:183], v[212:215], v[32:35]
	s_setprio 0
	s_barrier
	s_add_i32 s24, s46, s94
	s_add_u32 s98, s48, 0x80
	s_addc_u32 s99, s49, 0
	s_mov_b32 m0, s24
	ds_read_b128 v[184:187], v159 offset:49152
	global_load_lds_dwordx4 v132, s[98:99]
	s_add_i32 m0, s24, 0x2000
	s_add_u32 s24, s48, 0x80080
	s_addc_u32 s25, s49, 0
	s_add_i32 s46, s47, s94
	global_load_lds_dwordx4 v128, s[98:99]
	s_mov_b32 m0, s46
	ds_read_b128 v[188:191], v159 offset:50176
	global_load_lds_dwordx4 v132, s[24:25]
	s_add_i32 m0, s46, 0x2000
	ds_read_b128 v[192:195], v159 offset:51200
	global_load_lds_dwordx4 v128, s[24:25]
	s_add_u32 s100, s50, 0x80
	s_addc_u32 s101, s51, 0
	s_mov_b32 m0, s29
	ds_read_b128 v[196:199], v159 offset:52224
	global_load_lds_dwordx4 v134, s[100:101]
	s_mov_b32 m0, s34
	ds_read_b128 v[200:203], v159 offset:53248
	global_load_lds_dwordx4 v130, s[100:101]
	ds_read_b128 v[204:207], v159 offset:54272
	ds_read_b128 v[208:211], v159 offset:55296
	ds_read_b128 v[212:215], v159 offset:56320
	s_waitcnt vmcnt(8)
	s_waitcnt lgkmcnt(0)
	s_barrier
	s_setprio 1
	s_waitcnt lgkmcnt(0)
	v_mfma_f32_16x16x32_bf16 v[92:95], v[144:147], v[184:187], v[92:95]
	v_mfma_f32_16x16x32_bf16 v[88:91], v[160:163], v[184:187], v[88:91]
	v_mfma_f32_16x16x32_bf16 v[84:87], v[144:147], v[192:195], v[84:87]
	v_mfma_f32_16x16x32_bf16 v[80:83], v[160:163], v[192:195], v[80:83]
	v_mfma_f32_16x16x32_bf16 v[72:75], v[144:147], v[200:203], v[72:75]
	v_mfma_f32_16x16x32_bf16 v[68:71], v[160:163], v[200:203], v[68:71]
	v_mfma_f32_16x16x32_bf16 v[60:63], v[144:147], v[208:211], v[60:63]
	v_mfma_f32_16x16x32_bf16 v[52:55], v[160:163], v[208:211], v[52:55]
	v_mfma_f32_16x16x32_bf16 v[92:95], v[148:151], v[188:191], v[92:95]
	v_mfma_f32_16x16x32_bf16 v[88:91], v[164:167], v[188:191], v[88:91]
	v_mfma_f32_16x16x32_bf16 v[84:87], v[148:151], v[196:199], v[84:87]
	v_mfma_f32_16x16x32_bf16 v[80:83], v[164:167], v[196:199], v[80:83]
	v_mfma_f32_16x16x32_bf16 v[72:75], v[148:151], v[204:207], v[72:75]
	v_mfma_f32_16x16x32_bf16 v[68:71], v[164:167], v[204:207], v[68:71]
	v_mfma_f32_16x16x32_bf16 v[60:63], v[148:151], v[212:215], v[60:63]
	v_mfma_f32_16x16x32_bf16 v[52:55], v[164:167], v[212:215], v[52:55]
	s_setprio 0
	s_setprio 1
	v_mfma_f32_16x16x32_bf16 v[28:31], v[168:171], v[184:187], v[28:31]
	v_mfma_f32_16x16x32_bf16 v[24:27], v[176:179], v[184:187], v[24:27]
	v_mfma_f32_16x16x32_bf16 v[20:23], v[168:171], v[192:195], v[20:23]
	v_mfma_f32_16x16x32_bf16 v[16:19], v[176:179], v[192:195], v[16:19]
	v_mfma_f32_16x16x32_bf16 v[12:15], v[168:171], v[200:203], v[12:15]
	v_mfma_f32_16x16x32_bf16 v[8:11], v[176:179], v[200:203], v[8:11]
	v_mfma_f32_16x16x32_bf16 v[4:7], v[168:171], v[208:211], v[4:7]
	v_mfma_f32_16x16x32_bf16 v[0:3], v[176:179], v[208:211], v[0:3]
	v_mfma_f32_16x16x32_bf16 v[28:31], v[172:175], v[188:191], v[28:31]
	v_mfma_f32_16x16x32_bf16 v[24:27], v[180:183], v[188:191], v[24:27]
	v_mfma_f32_16x16x32_bf16 v[20:23], v[172:175], v[196:199], v[20:23]
	v_mfma_f32_16x16x32_bf16 v[16:19], v[180:183], v[196:199], v[16:19]
	v_mfma_f32_16x16x32_bf16 v[12:15], v[172:175], v[204:207], v[12:15]
	v_mfma_f32_16x16x32_bf16 v[8:11], v[180:183], v[204:207], v[8:11]
	v_mfma_f32_16x16x32_bf16 v[4:7], v[172:175], v[212:215], v[4:7]
	v_mfma_f32_16x16x32_bf16 v[0:3], v[180:183], v[212:215], v[0:3]
	s_setprio 0
	s_add_i32 s54, s54, 2
	s_add_u32 s52, s52, 0x100
	s_addc_u32 s53, s53, 0
	s_cmp_gt_u32 s54, 29
	s_mov_b64 s[46:47], s[6:7]
	s_barrier
	s_cbranch_scc0 .LBB0_1727
	s_and_b64 vcc, exec, s[22:23]
	s_cbranch_vccz .LBB0_1730
	s_barrier

; #define PG8_STAGE(bufoff, gbase, voff) do { _Pragma("unroll") for (int _i = 0; _i < 2; ++_i) \
;         __builtin_amdgcn_global_load_lds((const unsigned*)((const char*)(gbase) + (voff)[_i]), (LAS unsigned*)(lds + (bufoff) + ldsw + _i * 8192), 16, 0, 0); } while (0)
; #define PG8_LDA(dst, b, h) do { _Pragma("unroll") for (int m = 0; m < 4; ++m) _Pragma("unroll") for (int k = 0; k < 2; ++k) dst[m][k] = *(const LAS bf16x8*)(lds + PG8_SA(b, h) + aoff + m * 2048 + k * 1024); } while (0)
; #define PG8_LDB(dst, b, h) do { _Pragma("unroll") for (int n = 0; n < 2; ++n) _Pragma("unroll") for (int k = 0; k < 2; ++k) dst[n][k] = *(const LAS bf16x8*)(lds + PG8_SB(b, h) + boff + n * 2048 + k * 1024); } while (0)
; #define PG8_MMA(ai, bj, At, Bt) do { __builtin_amdgcn_s_setprio(1); _Pragma("unroll") for (int m = 0; m < 4; ++m) _Pragma("unroll") for (int n = 0; n < 2; ++n) _Pragma("unroll") for (int k = 0; k < 2; ++k) \
;         acc[ai][bj][m][n] = __builtin_amdgcn_mfma_f32_16x16x32_bf16(Bt[n][k], At[m][k], acc[ai][bj][m][n], 0, 0, 0); __builtin_amdgcn_s_setprio(0); } while (0)
; #define PG8_WAIT_V(n) asm volatile("s_waitcnt vmcnt(" #n ")" ::: "memory")
; #define PG8_WAIT_L(n) asm volatile("s_waitcnt lgkmcnt(" #n ")" ::: "memory")
; #define PG8_BAR __builtin_amdgcn_s_barrier()
; #define PG8_SCHED __builtin_amdgcn_sched_barrier(0)
; template <class Epi>
; __device__ __forceinline__ void gemm_phase(LAS unsigned char* lds, const Gemm g, const StaticOrder& S, const Epi& E, const int wid) {
;     ...
;             PG8_LDB(B0, 0, 0); PG8_LDB(B1, 0, 1); PG8_SCHED; PG8_LDA(At, 0, 0); PG8_STAGE(PG8_SA(1, 1), a1 + hstepA, voffA);
;             PG8_WAIT_V(8); PG8_WAIT_L(0); PG8_BAR; PG8_MMA(0, 0, At, B0); PG8_MMA(0, 1, At, B1); PG8_BAR; PG8_SCHED;
;             PG8_LDA(At, 0, 1); PG8_STAGE(PG8_SB(0, 0), b2, voffB); PG8_STAGE(PG8_SB(0, 1), b2 + hstepB, voffB); PG8_STAGE(PG8_SA(0, 0), a2, voffA);
;             PG8_WAIT_V(8); PG8_WAIT_L(0); PG8_BAR; PG8_MMA(1, 0, At, B0); PG8_MMA(1, 1, At, B1); PG8_BAR; PG8_SCHED;
;             PG8_LDB(B0, 1, 0); PG8_LDB(B1, 1, 1); PG8_SCHED; PG8_LDA(At, 1, 0); PG8_STAGE(PG8_SA(0, 1), a2 + hstepA, voffA);
;             PG8_WAIT_V(8); PG8_WAIT_L(0); PG8_BAR; PG8_MMA(0, 0, At, B0); PG8_MMA(0, 1, At, B1); PG8_BAR; PG8_SCHED;
.LBB0_1773:
	ds_read_b128 v[150:153], v147
	ds_read_b128 v[154:157], v147 offset:1024
	ds_read_b128 v[158:161], v147 offset:2048
	ds_read_b128 v[162:165], v147 offset:3072
	ds_read_b128 v[166:169], v148
	ds_read_b128 v[170:173], v148 offset:1024
	ds_read_b128 v[174:177], v148 offset:2048
	ds_read_b128 v[178:181], v148 offset:3072
	s_add_u32 s6, s42, 0x100
	s_addc_u32 s7, s43, 0
	s_cmp_eq_u32 s54, 28
	s_cselect_b32 s47, s21, s7
	s_cselect_b32 s46, s20, s6
	s_cselect_b32 s45, s19, s53
	s_cselect_b32 s44, s51, s52
	s_add_i32 m0, s15, 0xc000
	ds_read_b128 v[182:185], v149
	global_load_lds_dwordx4 v136, s[42:43]
	s_add_i32 m0, s15, 0xe000
	ds_read_b128 v[186:189], v149 offset:1024
	global_load_lds_dwordx4 v138, s[42:43]
	ds_read_b128 v[190:193], v149 offset:2048
	ds_read_b128 v[194:197], v149 offset:3072
	ds_read_b128 v[198:201], v149 offset:4096
	ds_read_b128 v[202:205], v149 offset:5120
	ds_read_b128 v[206:209], v149 offset:6144
	ds_read_b128 v[210:213], v149 offset:7168
	s_waitcnt vmcnt(8)
	s_waitcnt lgkmcnt(0)
	s_barrier
	s_setprio 1
	s_waitcnt lgkmcnt(0)
	v_mfma_f32_16x16x32_bf16 v[124:127], v[150:153], v[182:185], v[124:127]
	v_mfma_f32_16x16x32_bf16 v[120:123], v[158:161], v[182:185], v[120:123]
	v_mfma_f32_16x16x32_bf16 v[108:111], v[150:153], v[190:193], v[108:111]
	v_mfma_f32_16x16x32_bf16 v[104:107], v[158:161], v[190:193], v[104:107]
	v_mfma_f32_16x16x32_bf16 v[92:95], v[150:153], v[198:201], v[92:95]
	v_mfma_f32_16x16x32_bf16 v[88:91], v[158:161], v[198:201], v[88:91]
	v_mfma_f32_16x16x32_bf16 v[76:79], v[150:153], v[206:209], v[76:79]
	v_mfma_f32_16x16x32_bf16 v[72:75], v[158:161], v[206:209], v[72:75]
	v_mfma_f32_16x16x32_bf16 v[124:127], v[154:157], v[186:189], v[124:127]
	v_mfma_f32_16x16x32_bf16 v[120:123], v[162:165], v[186:189], v[120:123]
	v_mfma_f32_16x16x32_bf16 v[108:111], v[154:157], v[194:197], v[108:111]
	v_mfma_f32_16x16x32_bf16 v[104:107], v[162:165], v[194:197], v[104:107]
	v_mfma_f32_16x16x32_bf16 v[92:95], v[154:157], v[202:205], v[92:95]
	v_mfma_f32_16x16x32_bf16 v[88:91], v[162:165], v[202:205], v[88:91]
	v_mfma_f32_16x16x32_bf16 v[76:79], v[154:157], v[210:213], v[76:79]
	v_mfma_f32_16x16x32_bf16 v[72:75], v[162:165], v[210:213], v[72:75]
	s_setprio 0
	s_setprio 1
	v_mfma_f32_16x16x32_bf16 v[116:119], v[166:169], v[182:185], v[116:119]
	v_mfma_f32_16x16x32_bf16 v[112:115], v[174:177], v[182:185], v[112:115]
	v_mfma_f32_16x16x32_bf16 v[100:103], v[166:169], v[190:193], v[100:103]
	v_mfma_f32_16x16x32_bf16 v[96:99], v[174:177], v[190:193], v[96:99]
	v_mfma_f32_16x16x32_bf16 v[84:87], v[166:169], v[198:201], v[84:87]
	v_mfma_f32_16x16x32_bf16 v[80:83], v[174:177], v[198:201], v[80:83]
	v_mfma_f32_16x16x32_bf16 v[68:71], v[166:169], v[206:209], v[68:71]
	v_mfma_f32_16x16x32_bf16 v[64:67], v[174:177], v[206:209], v[64:67]
	v_mfma_f32_16x16x32_bf16 v[116:119], v[170:173], v[186:189], v[116:119]
	v_mfma_f32_16x16x32_bf16 v[112:115], v[178:181], v[186:189], v[112:115]
	v_mfma_f32_16x16x32_bf16 v[100:103], v[170:173], v[194:197], v[100:103]
	v_mfma_f32_16x16x32_bf16 v[96:99], v[178:181], v[194:197], v[96:99]
	v_mfma_f32_16x16x32_bf16 v[84:87], v[170:173], v[202:205], v[84:87]
	v_mfma_f32_16x16x32_bf16 v[80:83], v[178:181], v[202:205], v[80:83]
	v_mfma_f32_16x16x32_bf16 v[68:71], v[170:173], v[210:213], v[68:71]
	v_mfma_f32_16x16x32_bf16 v[64:67], v[178:181], v[210:213], v[64:67]
	s_setprio 0
	s_barrier
	s_add_i32 s24, s36, s94
	s_mov_b32 m0, s24
	ds_read_b128 v[182:185], v149 offset:16384
	global_load_lds_dwordx4 v132, s[44:45]
	s_add_i32 m0, s24, 0x2000
	s_add_u32 s24, s44, 0x80000
	s_addc_u32 s25, s45, 0
	s_add_i32 s42, s37, s94
	global_load_lds_dwordx4 v128, s[44:45]
	s_mov_b32 m0, s42
	ds_read_b128 v[186:189], v149 offset:17408
	global_load_lds_dwordx4 v132, s[24:25]
	s_add_i32 m0, s42, 0x2000
	ds_read_b128 v[190:193], v149 offset:18432
	global_load_lds_dwordx4 v128, s[24:25]
	s_mov_b32 m0, s15
	ds_read_b128 v[194:197], v149 offset:19456
	global_load_lds_dwordx4 v134, s[46:47]
	s_mov_b32 m0, s26
	ds_read_b128 v[198:201], v149 offset:20480
	global_load_lds_dwordx4 v130, s[46:47]
	ds_read_b128 v[202:205], v149 offset:21504
	ds_read_b128 v[206:209], v149 offset:22528
	ds_read_b128 v[210:213], v149 offset:23552
	s_waitcnt vmcnt(8)
	s_waitcnt lgkmcnt(0)
	s_barrier
	s_setprio 1
	s_waitcnt lgkmcnt(0)
	v_mfma_f32_16x16x32_bf16 v[60:63], v[150:153], v[182:185], v[60:63]
	v_mfma_f32_16x16x32_bf16 v[56:59], v[158:161], v[182:185], v[56:59]
	v_mfma_f32_16x16x32_bf16 v[44:47], v[150:153], v[190:193], v[44:47]
	v_mfma_f32_16x16x32_bf16 v[40:43], v[158:161], v[190:193], v[40:43]
	v_mfma_f32_16x16x32_bf16 v[28:31], v[150:153], v[198:201], v[28:31]
	v_mfma_f32_16x16x32_bf16 v[24:27], v[158:161], v[198:201], v[24:27]
	v_mfma_f32_16x16x32_bf16 v[12:15], v[150:153], v[206:209], v[12:15]
	v_mfma_f32_16x16x32_bf16 v[8:11], v[158:161], v[206:209], v[8:11]
	v_mfma_f32_16x16x32_bf16 v[60:63], v[154:157], v[186:189], v[60:63]
	v_mfma_f32_16x16x32_bf16 v[56:59], v[162:165], v[186:189], v[56:59]
	v_mfma_f32_16x16x32_bf16 v[44:47], v[154:157], v[194:197], v[44:47]
	v_mfma_f32_16x16x32_bf16 v[40:43], v[162:165], v[194:197], v[40:43]
	v_mfma_f32_16x16x32_bf16 v[28:31], v[154:157], v[202:205], v[28:31]
	v_mfma_f32_16x16x32_bf16 v[24:27], v[162:165], v[202:205], v[24:27]
	v_mfma_f32_16x16x32_bf16 v[12:15], v[154:157], v[210:213], v[12:15]
	v_mfma_f32_16x16x32_bf16 v[8:11], v[162:165], v[210:213], v[8:11]
	s_setprio 0
	s_setprio 1
	v_mfma_f32_16x16x32_bf16 v[52:55], v[166:169], v[182:185], v[52:55]
	v_mfma_f32_16x16x32_bf16 v[48:51], v[174:177], v[182:185], v[48:51]
	v_mfma_f32_16x16x32_bf16 v[36:39], v[166:169], v[190:193], v[36:39]
	v_mfma_f32_16x16x32_bf16 v[32:35], v[174:177], v[190:193], v[32:35]
	v_mfma_f32_16x16x32_bf16 v[20:23], v[166:169], v[198:201], v[20:23]
	v_mfma_f32_16x16x32_bf16 v[16:19], v[174:177], v[198:201], v[16:19]
	v_mfma_f32_16x16x32_bf16 v[4:7], v[166:169], v[206:209], v[4:7]
	v_mfma_f32_16x16x32_bf16 v[0:3], v[174:177], v[206:209], v[0:3]
	v_mfma_f32_16x16x32_bf16 v[52:55], v[170:173], v[186:189], v[52:55]
	v_mfma_f32_16x16x32_bf16 v[48:51], v[178:181], v[186:189], v[48:51]
	v_mfma_f32_16x16x32_bf16 v[36:39], v[170:173], v[194:197], v[36:39]
	v_mfma_f32_16x16x32_bf16 v[32:35], v[178:181], v[194:197], v[32:35]
	v_mfma_f32_16x16x32_bf16 v[20:23], v[170:173], v[202:205], v[20:23]
	v_mfma_f32_16x16x32_bf16 v[16:19], v[178:181], v[202:205], v[16:19]
	v_mfma_f32_16x16x32_bf16 v[4:7], v[170:173], v[210:213], v[4:7]
	v_mfma_f32_16x16x32_bf16 v[0:3], v[178:181], v[210:213], v[0:3]
	s_setprio 0
	s_barrier
; #define PG8_STAGE(bufoff, gbase, voff) do { _Pragma("unroll") for (int _i = 0; _i < 2; ++_i) \
;         __builtin_amdgcn_global_load_lds((const unsigned*)((const char*)(gbase) + (voff)[_i]), (LAS unsigned*)(lds + (bufoff) + ldsw + _i * 8192), 16, 0, 0); } while (0)
; #define PG8_LDA(dst, b, h) do { _Pragma("unroll") for (int m = 0; m < 4; ++m) _Pragma("unroll") for (int k = 0; k < 2; ++k) dst[m][k] = *(const LAS bf16x8*)(lds + PG8_SA(b, h) + aoff + m * 2048 + k * 1024); } while (0)
; #define PG8_LDB(dst, b, h) do { _Pragma("unroll") for (int n = 0; n < 2; ++n) _Pragma("unroll") for (int k = 0; k < 2; ++k) dst[n][k] = *(const LAS bf16x8*)(lds + PG8_SB(b, h) + boff + n * 2048 + k * 1024); } while (0)
; #define PG8_MMA(ai, bj, At, Bt) do { __builtin_amdgcn_s_setprio(1); _Pragma("unroll") for (int m = 0; m < 4; ++m) _Pragma("unroll") for (int n = 0; n < 2; ++n) _Pragma("unroll") for (int k = 0; k < 2; ++k) \
;         acc[ai][bj][m][n] = __builtin_amdgcn_mfma_f32_16x16x32_bf16(Bt[n][k], At[m][k], acc[ai][bj][m][n], 0, 0, 0); __builtin_amdgcn_s_setprio(0); } while (0)
; #define PG8_WAIT_V(n) asm volatile("s_waitcnt vmcnt(" #n ")" ::: "memory")
; #define PG8_WAIT_L(n) asm volatile("s_waitcnt lgkmcnt(" #n ")" ::: "memory")
; #define PG8_BAR __builtin_amdgcn_s_barrier()
; #define PG8_SCHED __builtin_amdgcn_sched_barrier(0)
; template <class Epi>
; __device__ __forceinline__ void gemm_phase(LAS unsigned char* lds, const Gemm g, const StaticOrder& S, const Epi& E, const int wid) {
;     ...
;             PG8_LDB(B0, 1, 0); PG8_LDB(B1, 1, 1); PG8_SCHED; PG8_LDA(At, 1, 0); PG8_STAGE(PG8_SA(0, 1), a2 + hstepA, voffA);
;             PG8_WAIT_V(8); PG8_WAIT_L(0); PG8_BAR; PG8_MMA(0, 0, At, B0); PG8_MMA(0, 1, At, B1); PG8_BAR; PG8_SCHED;
;             PG8_LDA(At, 1, 1); PG8_STAGE(PG8_SB(1, 0), b3, voffB); PG8_STAGE(PG8_SB(1, 1), b3 + hstepB, voffB); PG8_STAGE(PG8_SA(1, 0), a3, voffA);
;             PG8_WAIT_V(8); PG8_WAIT_L(0); PG8_BAR; PG8_MMA(1, 0, At, B0); PG8_MMA(1, 1, At, B1); PG8_BAR; PG8_SCHED;
;         }
	s_add_i32 s42, 0, 0x18000
	s_add_i32 s43, 0, 0x1c000
	v_add_u32_e32 v162, s42, v144
	v_add_u32_e32 v178, s43, v144
	ds_read_b128 v[150:153], v162
	ds_read_b128 v[154:157], v162 offset:1024
	ds_read_b128 v[158:161], v162 offset:2048
	ds_read_b128 v[162:165], v162 offset:3072
	ds_read_b128 v[166:169], v178
	ds_read_b128 v[170:173], v178 offset:1024
	ds_read_b128 v[174:177], v178 offset:2048
	ds_read_b128 v[178:181], v178 offset:3072
	s_add_u32 s24, s46, 0x80000
	s_addc_u32 s25, s47, 0
	s_mov_b32 m0, s27
	ds_read_b128 v[182:185], v149 offset:32768
	global_load_lds_dwordx4 v134, s[24:25]
	s_mov_b32 m0, s28
	ds_read_b128 v[186:189], v149 offset:33792
	global_load_lds_dwordx4 v130, s[24:25]
	ds_read_b128 v[190:193], v149 offset:34816
	ds_read_b128 v[194:197], v149 offset:35840
	ds_read_b128 v[198:201], v149 offset:36864
	ds_read_b128 v[202:205], v149 offset:37888
	ds_read_b128 v[206:209], v149 offset:38912
	ds_read_b128 v[210:213], v149 offset:39936
	s_waitcnt vmcnt(8)
	s_waitcnt lgkmcnt(0)
	s_barrier
	s_setprio 1
	s_waitcnt lgkmcnt(0)
	v_mfma_f32_16x16x32_bf16 v[124:127], v[150:153], v[182:185], v[124:127]
	v_mfma_f32_16x16x32_bf16 v[120:123], v[158:161], v[182:185], v[120:123]
	v_mfma_f32_16x16x32_bf16 v[108:111], v[150:153], v[190:193], v[108:111]
	v_mfma_f32_16x16x32_bf16 v[104:107], v[158:161], v[190:193], v[104:107]
	v_mfma_f32_16x16x32_bf16 v[92:95], v[150:153], v[198:201], v[92:95]
	v_mfma_f32_16x16x32_bf16 v[88:91], v[158:161], v[198:201], v[88:91]
	v_mfma_f32_16x16x32_bf16 v[76:79], v[150:153], v[206:209], v[76:79]
	v_mfma_f32_16x16x32_bf16 v[72:75], v[158:161], v[206:209], v[72:75]
	v_mfma_f32_16x16x32_bf16 v[124:127], v[154:157], v[186:189], v[124:127]
	v_mfma_f32_16x16x32_bf16 v[120:123], v[162:165], v[186:189], v[120:123]
	v_mfma_f32_16x16x32_bf16 v[108:111], v[154:157], v[194:197], v[108:111]
	v_mfma_f32_16x16x32_bf16 v[104:107], v[162:165], v[194:197], v[104:107]
	v_mfma_f32_16x16x32_bf16 v[92:95], v[154:157], v[202:205], v[92:95]
	v_mfma_f32_16x16x32_bf16 v[88:91], v[162:165], v[202:205], v[88:91]
	v_mfma_f32_16x16x32_bf16 v[76:79], v[154:157], v[210:213], v[76:79]
	v_mfma_f32_16x16x32_bf16 v[72:75], v[162:165], v[210:213], v[72:75]
	s_setprio 0
	s_setprio 1
	v_mfma_f32_16x16x32_bf16 v[116:119], v[166:169], v[182:185], v[116:119]
	v_mfma_f32_16x16x32_bf16 v[112:115], v[174:177], v[182:185], v[112:115]
	v_mfma_f32_16x16x32_bf16 v[100:103], v[166:169], v[190:193], v[100:103]
	v_mfma_f32_16x16x32_bf16 v[96:99], v[174:177], v[190:193], v[96:99]
	v_mfma_f32_16x16x32_bf16 v[84:87], v[166:169], v[198:201], v[84:87]
	v_mfma_f32_16x16x32_bf16 v[80:83], v[174:177], v[198:201], v[80:83]
	v_mfma_f32_16x16x32_bf16 v[68:71], v[166:169], v[206:209], v[68:71]
	v_mfma_f32_16x16x32_bf16 v[64:67], v[174:177], v[206:209], v[64:67]
	v_mfma_f32_16x16x32_bf16 v[116:119], v[170:173], v[186:189], v[116:119]
	v_mfma_f32_16x16x32_bf16 v[112:115], v[178:181], v[186:189], v[112:115]
	v_mfma_f32_16x16x32_bf16 v[100:103], v[170:173], v[194:197], v[100:103]
	v_mfma_f32_16x16x32_bf16 v[96:99], v[178:181], v[194:197], v[96:99]
	v_mfma_f32_16x16x32_bf16 v[84:87], v[170:173], v[202:205], v[84:87]
	v_mfma_f32_16x16x32_bf16 v[80:83], v[178:181], v[202:205], v[80:83]
	v_mfma_f32_16x16x32_bf16 v[68:71], v[170:173], v[210:213], v[68:71]
	v_mfma_f32_16x16x32_bf16 v[64:67], v[178:181], v[210:213], v[64:67]
	s_setprio 0
	s_barrier
	s_add_i32 s24, s42, s94
	s_add_u32 s98, s44, 0x80
	s_addc_u32 s99, s45, 0
	s_mov_b32 m0, s24
	ds_read_b128 v[182:185], v149 offset:49152
	global_load_lds_dwordx4 v132, s[98:99]
	s_add_i32 m0, s24, 0x2000
	s_add_u32 s24, s44, 0x80080
	s_addc_u32 s25, s45, 0
	s_add_i32 s42, s43, s94
	global_load_lds_dwordx4 v128, s[98:99]
	s_mov_b32 m0, s42
	ds_read_b128 v[186:189], v149 offset:50176
	global_load_lds_dwordx4 v132, s[24:25]
	s_add_i32 m0, s42, 0x2000
	ds_read_b128 v[190:193], v149 offset:51200
	global_load_lds_dwordx4 v128, s[24:25]
	s_add_u32 s100, s46, 0x80
	s_addc_u32 s101, s47, 0
	s_mov_b32 m0, s34
	ds_read_b128 v[194:197], v149 offset:52224
	global_load_lds_dwordx4 v134, s[100:101]
	s_mov_b32 m0, s35
	ds_read_b128 v[198:201], v149 offset:53248
	global_load_lds_dwordx4 v130, s[100:101]
	ds_read_b128 v[202:205], v149 offset:54272
	ds_read_b128 v[206:209], v149 offset:55296
	ds_read_b128 v[210:213], v149 offset:56320
	s_waitcnt vmcnt(8)
	s_waitcnt lgkmcnt(0)
	s_barrier
	s_setprio 1
	s_waitcnt lgkmcnt(0)
	v_mfma_f32_16x16x32_bf16 v[60:63], v[150:153], v[182:185], v[60:63]
	v_mfma_f32_16x16x32_bf16 v[56:59], v[158:161], v[182:185], v[56:59]
	v_mfma_f32_16x16x32_bf16 v[44:47], v[150:153], v[190:193], v[44:47]
	v_mfma_f32_16x16x32_bf16 v[40:43], v[158:161], v[190:193], v[40:43]
	v_mfma_f32_16x16x32_bf16 v[28:31], v[150:153], v[198:201], v[28:31]
	v_mfma_f32_16x16x32_bf16 v[24:27], v[158:161], v[198:201], v[24:27]
	v_mfma_f32_16x16x32_bf16 v[12:15], v[150:153], v[206:209], v[12:15]
	v_mfma_f32_16x16x32_bf16 v[8:11], v[158:161], v[206:209], v[8:11]
	v_mfma_f32_16x16x32_bf16 v[60:63], v[154:157], v[186:189], v[60:63]
	v_mfma_f32_16x16x32_bf16 v[56:59], v[162:165], v[186:189], v[56:59]
	v_mfma_f32_16x16x32_bf16 v[44:47], v[154:157], v[194:197], v[44:47]
	v_mfma_f32_16x16x32_bf16 v[40:43], v[162:165], v[194:197], v[40:43]
	v_mfma_f32_16x16x32_bf16 v[28:31], v[154:157], v[202:205], v[28:31]
	v_mfma_f32_16x16x32_bf16 v[24:27], v[162:165], v[202:205], v[24:27]
	v_mfma_f32_16x16x32_bf16 v[12:15], v[154:157], v[210:213], v[12:15]
	v_mfma_f32_16x16x32_bf16 v[8:11], v[162:165], v[210:213], v[8:11]
	s_setprio 0
	s_setprio 1
	v_mfma_f32_16x16x32_bf16 v[52:55], v[166:169], v[182:185], v[52:55]
	v_mfma_f32_16x16x32_bf16 v[48:51], v[174:177], v[182:185], v[48:51]
	v_mfma_f32_16x16x32_bf16 v[36:39], v[166:169], v[190:193], v[36:39]
	v_mfma_f32_16x16x32_bf16 v[32:35], v[174:177], v[190:193], v[32:35]
	v_mfma_f32_16x16x32_bf16 v[20:23], v[166:169], v[198:201], v[20:23]
	v_mfma_f32_16x16x32_bf16 v[16:19], v[174:177], v[198:201], v[16:19]
	v_mfma_f32_16x16x32_bf16 v[4:7], v[166:169], v[206:209], v[4:7]
	v_mfma_f32_16x16x32_bf16 v[0:3], v[174:177], v[206:209], v[0:3]
	v_mfma_f32_16x16x32_bf16 v[52:55], v[170:173], v[186:189], v[52:55]
	v_mfma_f32_16x16x32_bf16 v[48:51], v[178:181], v[186:189], v[48:51]
	v_mfma_f32_16x16x32_bf16 v[36:39], v[170:173], v[194:197], v[36:39]
	v_mfma_f32_16x16x32_bf16 v[32:35], v[178:181], v[194:197], v[32:35]
	v_mfma_f32_16x16x32_bf16 v[20:23], v[170:173], v[202:205], v[20:23]
	v_mfma_f32_16x16x32_bf16 v[16:19], v[178:181], v[202:205], v[16:19]
	v_mfma_f32_16x16x32_bf16 v[4:7], v[170:173], v[210:213], v[4:7]
	v_mfma_f32_16x16x32_bf16 v[0:3], v[178:181], v[210:213], v[0:3]
	s_setprio 0
	s_add_i32 s54, s54, 2
	s_add_u32 s52, s52, 0x100
	s_addc_u32 s53, s53, 0
	s_cmp_gt_u32 s54, 29
	s_mov_b64 s[42:43], s[6:7]
	s_barrier
	s_cbranch_scc0 .LBB0_1773
	s_and_b64 vcc, exec, s[22:23]
	s_cbranch_vccz .LBB0_1776
	s_barrier

; #define PG8_STAGE(bufoff, gbase, voff) do { _Pragma("unroll") for (int _i = 0; _i < 2; ++_i) \
;         __builtin_amdgcn_global_load_lds((const unsigned*)((const char*)(gbase) + (voff)[_i]), (LAS unsigned*)(lds + (bufoff) + ldsw + _i * 8192), 16, 0, 0); } while (0)
; #define PG8_LDA(dst, b, h) do { _Pragma("unroll") for (int m = 0; m < 4; ++m) _Pragma("unroll") for (int k = 0; k < 2; ++k) dst[m][k] = *(const LAS bf16x8*)(lds + PG8_SA(b, h) + aoff + m * 2048 + k * 1024); } while (0)
; #define PG8_LDB(dst, b, h) do { _Pragma("unroll") for (int n = 0; n < 2; ++n) _Pragma("unroll") for (int k = 0; k < 2; ++k) dst[n][k] = *(const LAS bf16x8*)(lds + PG8_SB(b, h) + boff + n * 2048 + k * 1024); } while (0)
; #define PG8_MMA(ai, bj, At, Bt) do { __builtin_amdgcn_s_setprio(1); _Pragma("unroll") for (int m = 0; m < 4; ++m) _Pragma("unroll") for (int n = 0; n < 2; ++n) _Pragma("unroll") for (int k = 0; k < 2; ++k) \
;         acc[ai][bj][m][n] = __builtin_amdgcn_mfma_f32_16x16x32_bf16(Bt[n][k], At[m][k], acc[ai][bj][m][n], 0, 0, 0); __builtin_amdgcn_s_setprio(0); } while (0)
; #define PG8_WAIT_V(n) asm volatile("s_waitcnt vmcnt(" #n ")" ::: "memory")
; #define PG8_WAIT_L(n) asm volatile("s_waitcnt lgkmcnt(" #n ")" ::: "memory")
; #define PG8_BAR __builtin_amdgcn_s_barrier()
; #define PG8_SCHED __builtin_amdgcn_sched_barrier(0)
; template <class Epi>
; __device__ __forceinline__ void gemm_phase(LAS unsigned char* lds, const Gemm g, const StaticOrder& S, const Epi& E, const int wid) {
;     ...
;             PG8_LDB(B0, 0, 0); PG8_LDB(B1, 0, 1); PG8_SCHED; PG8_LDA(At, 0, 0); PG8_STAGE(PG8_SA(1, 1), a1 + hstepA, voffA);
;             PG8_WAIT_V(8); PG8_WAIT_L(0); PG8_BAR; PG8_MMA(0, 0, At, B0); PG8_MMA(0, 1, At, B1); PG8_BAR; PG8_SCHED;
;             PG8_LDA(At, 0, 1); PG8_STAGE(PG8_SB(0, 0), b2, voffB); PG8_STAGE(PG8_SB(0, 1), b2 + hstepB, voffB); PG8_STAGE(PG8_SA(0, 0), a2, voffA);
;             PG8_WAIT_V(8); PG8_WAIT_L(0); PG8_BAR; PG8_MMA(1, 0, At, B0); PG8_MMA(1, 1, At, B1); PG8_BAR; PG8_SCHED;
;             PG8_LDB(B0, 1, 0); PG8_LDB(B1, 1, 1); PG8_SCHED; PG8_LDA(At, 1, 0); PG8_STAGE(PG8_SA(0, 1), a2 + hstepA, voffA);
;             PG8_WAIT_V(8); PG8_WAIT_L(0); PG8_BAR; PG8_MMA(0, 0, At, B0); PG8_MMA(0, 1, At, B1); PG8_BAR; PG8_SCHED;
.LBB0_1810:
	ds_read_b128 v[144:147], v153
	ds_read_b128 v[156:159], v153 offset:1024
	ds_read_b128 v[160:163], v153 offset:2048
	ds_read_b128 v[164:167], v153 offset:3072
	ds_read_b128 v[168:171], v154
	ds_read_b128 v[172:175], v154 offset:1024
	ds_read_b128 v[176:179], v154 offset:2048
	ds_read_b128 v[180:183], v154 offset:3072
	s_add_u32 s26, s20, 0x100
	s_addc_u32 s27, s21, 0
	s_cmpk_eq_i32 s45, 0x54
	s_cselect_b32 s31, s7, s27
	s_cselect_b32 s30, s6, s26
	s_cselect_b32 s29, s19, s44
	s_cselect_b32 s28, s18, s43
	s_add_i32 m0, s1, 0xc000
	ds_read_b128 v[184:187], v155
	global_load_lds_dwordx4 v136, s[20:21]
	s_add_i32 m0, s1, 0xe000
	ds_read_b128 v[188:191], v155 offset:1024
	global_load_lds_dwordx4 v138, s[20:21]
	ds_read_b128 v[192:195], v155 offset:2048
	ds_read_b128 v[196:199], v155 offset:3072
	ds_read_b128 v[200:203], v155 offset:4096
	ds_read_b128 v[204:207], v155 offset:5120
	ds_read_b128 v[208:211], v155 offset:6144
	ds_read_b128 v[212:215], v155 offset:7168
	s_waitcnt vmcnt(8)
	s_waitcnt lgkmcnt(0)
	s_barrier
	s_setprio 1
	s_waitcnt lgkmcnt(0)
	v_mfma_f32_16x16x32_bf16 v[124:127], v[144:147], v[184:187], v[124:127]
	v_mfma_f32_16x16x32_bf16 v[120:123], v[160:163], v[184:187], v[120:123]
	v_mfma_f32_16x16x32_bf16 v[116:119], v[144:147], v[192:195], v[116:119]
	v_mfma_f32_16x16x32_bf16 v[112:115], v[160:163], v[192:195], v[112:115]
	v_mfma_f32_16x16x32_bf16 v[108:111], v[144:147], v[200:203], v[108:111]
	v_mfma_f32_16x16x32_bf16 v[104:107], v[160:163], v[200:203], v[104:107]
	v_mfma_f32_16x16x32_bf16 v[100:103], v[144:147], v[208:211], v[100:103]
	v_mfma_f32_16x16x32_bf16 v[96:99], v[160:163], v[208:211], v[96:99]
	v_mfma_f32_16x16x32_bf16 v[124:127], v[156:159], v[188:191], v[124:127]
	v_mfma_f32_16x16x32_bf16 v[120:123], v[164:167], v[188:191], v[120:123]
	v_mfma_f32_16x16x32_bf16 v[116:119], v[156:159], v[196:199], v[116:119]
	v_mfma_f32_16x16x32_bf16 v[112:115], v[164:167], v[196:199], v[112:115]
	v_mfma_f32_16x16x32_bf16 v[108:111], v[156:159], v[204:207], v[108:111]
	v_mfma_f32_16x16x32_bf16 v[104:107], v[164:167], v[204:207], v[104:107]
	v_mfma_f32_16x16x32_bf16 v[100:103], v[156:159], v[212:215], v[100:103]
	v_mfma_f32_16x16x32_bf16 v[96:99], v[164:167], v[212:215], v[96:99]
	s_setprio 0
	s_setprio 1
	v_mfma_f32_16x16x32_bf16 v[68:71], v[168:171], v[184:187], v[68:71]
	v_mfma_f32_16x16x32_bf16 v[64:67], v[176:179], v[184:187], v[64:67]
	v_mfma_f32_16x16x32_bf16 v[52:55], v[168:171], v[192:195], v[52:55]
	v_mfma_f32_16x16x32_bf16 v[48:51], v[176:179], v[192:195], v[48:51]
	v_mfma_f32_16x16x32_bf16 v[44:47], v[168:171], v[200:203], v[44:47]
	v_mfma_f32_16x16x32_bf16 v[40:43], v[176:179], v[200:203], v[40:43]
	v_mfma_f32_16x16x32_bf16 v[36:39], v[168:171], v[208:211], v[36:39]
	v_mfma_f32_16x16x32_bf16 v[32:35], v[176:179], v[208:211], v[32:35]
	v_mfma_f32_16x16x32_bf16 v[68:71], v[172:175], v[188:191], v[68:71]
	v_mfma_f32_16x16x32_bf16 v[64:67], v[180:183], v[188:191], v[64:67]
	v_mfma_f32_16x16x32_bf16 v[52:55], v[172:175], v[196:199], v[52:55]
	v_mfma_f32_16x16x32_bf16 v[48:51], v[180:183], v[196:199], v[48:51]
	v_mfma_f32_16x16x32_bf16 v[44:47], v[172:175], v[204:207], v[44:47]
	v_mfma_f32_16x16x32_bf16 v[40:43], v[180:183], v[204:207], v[40:43]
	v_mfma_f32_16x16x32_bf16 v[36:39], v[172:175], v[212:215], v[36:39]
	v_mfma_f32_16x16x32_bf16 v[32:35], v[180:183], v[212:215], v[32:35]
	s_setprio 0
	s_barrier
	s_add_i32 s20, s0, s94
	s_mov_b32 m0, s20
	ds_read_b128 v[184:187], v155 offset:16384
	global_load_lds_dwordx4 v132, s[28:29]
	s_add_i32 m0, s20, 0x2000
	s_add_u32 s20, s28, 0x160000
	s_addc_u32 s21, s29, 0
	s_add_i32 s24, s38, s94
	global_load_lds_dwordx4 v128, s[28:29]
	s_mov_b32 m0, s24
	ds_read_b128 v[188:191], v155 offset:17408
	global_load_lds_dwordx4 v132, s[20:21]
	s_add_i32 m0, s24, 0x2000
	ds_read_b128 v[192:195], v155 offset:18432
	global_load_lds_dwordx4 v128, s[20:21]
	s_mov_b32 m0, s1
	ds_read_b128 v[196:199], v155 offset:19456
	global_load_lds_dwordx4 v134, s[30:31]
	s_mov_b32 m0, s12
	ds_read_b128 v[200:203], v155 offset:20480
	global_load_lds_dwordx4 v130, s[30:31]
	ds_read_b128 v[204:207], v155 offset:21504
	ds_read_b128 v[208:211], v155 offset:22528
	ds_read_b128 v[212:215], v155 offset:23552
	s_waitcnt vmcnt(8)
	s_waitcnt lgkmcnt(0)
	s_barrier
	s_setprio 1
	s_waitcnt lgkmcnt(0)
	v_mfma_f32_16x16x32_bf16 v[92:95], v[144:147], v[184:187], v[92:95]
	v_mfma_f32_16x16x32_bf16 v[88:91], v[160:163], v[184:187], v[88:91]
	v_mfma_f32_16x16x32_bf16 v[84:87], v[144:147], v[192:195], v[84:87]
	v_mfma_f32_16x16x32_bf16 v[80:83], v[160:163], v[192:195], v[80:83]
	v_mfma_f32_16x16x32_bf16 v[76:79], v[144:147], v[200:203], v[76:79]
	v_mfma_f32_16x16x32_bf16 v[72:75], v[160:163], v[200:203], v[72:75]
	v_mfma_f32_16x16x32_bf16 v[60:63], v[144:147], v[208:211], v[60:63]
	v_mfma_f32_16x16x32_bf16 v[56:59], v[160:163], v[208:211], v[56:59]
	v_mfma_f32_16x16x32_bf16 v[92:95], v[156:159], v[188:191], v[92:95]
	v_mfma_f32_16x16x32_bf16 v[88:91], v[164:167], v[188:191], v[88:91]
	v_mfma_f32_16x16x32_bf16 v[84:87], v[156:159], v[196:199], v[84:87]
	v_mfma_f32_16x16x32_bf16 v[80:83], v[164:167], v[196:199], v[80:83]
	v_mfma_f32_16x16x32_bf16 v[76:79], v[156:159], v[204:207], v[76:79]
	v_mfma_f32_16x16x32_bf16 v[72:75], v[164:167], v[204:207], v[72:75]
	v_mfma_f32_16x16x32_bf16 v[60:63], v[156:159], v[212:215], v[60:63]
	v_mfma_f32_16x16x32_bf16 v[56:59], v[164:167], v[212:215], v[56:59]
	s_setprio 0
	s_setprio 1
	v_mfma_f32_16x16x32_bf16 v[28:31], v[168:171], v[184:187], v[28:31]
	v_mfma_f32_16x16x32_bf16 v[24:27], v[176:179], v[184:187], v[24:27]
	v_mfma_f32_16x16x32_bf16 v[20:23], v[168:171], v[192:195], v[20:23]
	v_mfma_f32_16x16x32_bf16 v[16:19], v[176:179], v[192:195], v[16:19]
	v_mfma_f32_16x16x32_bf16 v[12:15], v[168:171], v[200:203], v[12:15]
	v_mfma_f32_16x16x32_bf16 v[8:11], v[176:179], v[200:203], v[8:11]
	v_mfma_f32_16x16x32_bf16 v[4:7], v[168:171], v[208:211], v[4:7]
	v_mfma_f32_16x16x32_bf16 v[0:3], v[176:179], v[208:211], v[0:3]
	v_mfma_f32_16x16x32_bf16 v[28:31], v[172:175], v[188:191], v[28:31]
	v_mfma_f32_16x16x32_bf16 v[24:27], v[180:183], v[188:191], v[24:27]
	v_mfma_f32_16x16x32_bf16 v[20:23], v[172:175], v[196:199], v[20:23]
	v_mfma_f32_16x16x32_bf16 v[16:19], v[180:183], v[196:199], v[16:19]
	v_mfma_f32_16x16x32_bf16 v[12:15], v[172:175], v[204:207], v[12:15]
	v_mfma_f32_16x16x32_bf16 v[8:11], v[180:183], v[204:207], v[8:11]
	v_mfma_f32_16x16x32_bf16 v[4:7], v[172:175], v[212:215], v[4:7]
	v_mfma_f32_16x16x32_bf16 v[0:3], v[180:183], v[212:215], v[0:3]
	s_setprio 0
	s_barrier
; #define PG8_STAGE(bufoff, gbase, voff) do { _Pragma("unroll") for (int _i = 0; _i < 2; ++_i) \
;         __builtin_amdgcn_global_load_lds((const unsigned*)((const char*)(gbase) + (voff)[_i]), (LAS unsigned*)(lds + (bufoff) + ldsw + _i * 8192), 16, 0, 0); } while (0)
; #define PG8_LDA(dst, b, h) do { _Pragma("unroll") for (int m = 0; m < 4; ++m) _Pragma("unroll") for (int k = 0; k < 2; ++k) dst[m][k] = *(const LAS bf16x8*)(lds + PG8_SA(b, h) + aoff + m * 2048 + k * 1024); } while (0)
; #define PG8_LDB(dst, b, h) do { _Pragma("unroll") for (int n = 0; n < 2; ++n) _Pragma("unroll") for (int k = 0; k < 2; ++k) dst[n][k] = *(const LAS bf16x8*)(lds + PG8_SB(b, h) + boff + n * 2048 + k * 1024); } while (0)
; #define PG8_MMA(ai, bj, At, Bt) do { __builtin_amdgcn_s_setprio(1); _Pragma("unroll") for (int m = 0; m < 4; ++m) _Pragma("unroll") for (int n = 0; n < 2; ++n) _Pragma("unroll") for (int k = 0; k < 2; ++k) \
;         acc[ai][bj][m][n] = __builtin_amdgcn_mfma_f32_16x16x32_bf16(Bt[n][k], At[m][k], acc[ai][bj][m][n], 0, 0, 0); __builtin_amdgcn_s_setprio(0); } while (0)
; #define PG8_WAIT_V(n) asm volatile("s_waitcnt vmcnt(" #n ")" ::: "memory")
; #define PG8_WAIT_L(n) asm volatile("s_waitcnt lgkmcnt(" #n ")" ::: "memory")
; #define PG8_BAR __builtin_amdgcn_s_barrier()
; #define PG8_SCHED __builtin_amdgcn_sched_barrier(0)
; template <class Epi>
; __device__ __forceinline__ void gemm_phase(LAS unsigned char* lds, const Gemm g, const StaticOrder& S, const Epi& E, const int wid) {
;     ...
;             PG8_LDB(B0, 1, 0); PG8_LDB(B1, 1, 1); PG8_SCHED; PG8_LDA(At, 1, 0); PG8_STAGE(PG8_SA(0, 1), a2 + hstepA, voffA);
;             PG8_WAIT_V(8); PG8_WAIT_L(0); PG8_BAR; PG8_MMA(0, 0, At, B0); PG8_MMA(0, 1, At, B1); PG8_BAR; PG8_SCHED;
;             PG8_LDA(At, 1, 1); PG8_STAGE(PG8_SB(1, 0), b3, voffB); PG8_STAGE(PG8_SB(1, 1), b3 + hstepB, voffB); PG8_STAGE(PG8_SA(1, 0), a3, voffA);
;             PG8_WAIT_V(8); PG8_WAIT_L(0); PG8_BAR; PG8_MMA(1, 0, At, B0); PG8_MMA(1, 1, At, B1); PG8_BAR; PG8_SCHED;
;         }
	s_add_i32 s24, 0, 0x18000
	s_add_i32 s25, 0, 0x1c000
	v_add_u32_e32 v164, s24, v150
	v_add_u32_e32 v180, s25, v150
	ds_read_b128 v[144:147], v164
	ds_read_b128 v[156:159], v164 offset:1024
	ds_read_b128 v[160:163], v164 offset:2048
	ds_read_b128 v[164:167], v164 offset:3072
	ds_read_b128 v[168:171], v180
	ds_read_b128 v[172:175], v180 offset:1024
	ds_read_b128 v[176:179], v180 offset:2048
	ds_read_b128 v[180:183], v180 offset:3072
	s_add_u32 s20, s30, 0x160000
	s_addc_u32 s21, s31, 0
	s_mov_b32 m0, s15
	ds_read_b128 v[184:187], v155 offset:32768
	global_load_lds_dwordx4 v134, s[20:21]
	s_mov_b32 m0, s34
	ds_read_b128 v[188:191], v155 offset:33792
	global_load_lds_dwordx4 v130, s[20:21]
	ds_read_b128 v[192:195], v155 offset:34816
	ds_read_b128 v[196:199], v155 offset:35840
	ds_read_b128 v[200:203], v155 offset:36864
	ds_read_b128 v[204:207], v155 offset:37888
	ds_read_b128 v[208:211], v155 offset:38912
	ds_read_b128 v[212:215], v155 offset:39936
	s_waitcnt vmcnt(8)
	s_waitcnt lgkmcnt(0)
	s_barrier
	s_setprio 1
	s_waitcnt lgkmcnt(0)
	v_mfma_f32_16x16x32_bf16 v[124:127], v[144:147], v[184:187], v[124:127]
	v_mfma_f32_16x16x32_bf16 v[120:123], v[160:163], v[184:187], v[120:123]
	v_mfma_f32_16x16x32_bf16 v[116:119], v[144:147], v[192:195], v[116:119]
	v_mfma_f32_16x16x32_bf16 v[112:115], v[160:163], v[192:195], v[112:115]
	v_mfma_f32_16x16x32_bf16 v[108:111], v[144:147], v[200:203], v[108:111]
	v_mfma_f32_16x16x32_bf16 v[104:107], v[160:163], v[200:203], v[104:107]
	v_mfma_f32_16x16x32_bf16 v[100:103], v[144:147], v[208:211], v[100:103]
	v_mfma_f32_16x16x32_bf16 v[96:99], v[160:163], v[208:211], v[96:99]
	v_mfma_f32_16x16x32_bf16 v[124:127], v[156:159], v[188:191], v[124:127]
	v_mfma_f32_16x16x32_bf16 v[120:123], v[164:167], v[188:191], v[120:123]
	v_mfma_f32_16x16x32_bf16 v[116:119], v[156:159], v[196:199], v[116:119]
	v_mfma_f32_16x16x32_bf16 v[112:115], v[164:167], v[196:199], v[112:115]
	v_mfma_f32_16x16x32_bf16 v[108:111], v[156:159], v[204:207], v[108:111]
	v_mfma_f32_16x16x32_bf16 v[104:107], v[164:167], v[204:207], v[104:107]
	v_mfma_f32_16x16x32_bf16 v[100:103], v[156:159], v[212:215], v[100:103]
	v_mfma_f32_16x16x32_bf16 v[96:99], v[164:167], v[212:215], v[96:99]
	s_setprio 0
	s_setprio 1
	v_mfma_f32_16x16x32_bf16 v[68:71], v[168:171], v[184:187], v[68:71]
	v_mfma_f32_16x16x32_bf16 v[64:67], v[176:179], v[184:187], v[64:67]
	v_mfma_f32_16x16x32_bf16 v[52:55], v[168:171], v[192:195], v[52:55]
	v_mfma_f32_16x16x32_bf16 v[48:51], v[176:179], v[192:195], v[48:51]
	v_mfma_f32_16x16x32_bf16 v[44:47], v[168:171], v[200:203], v[44:47]
	v_mfma_f32_16x16x32_bf16 v[40:43], v[176:179], v[200:203], v[40:43]
	v_mfma_f32_16x16x32_bf16 v[36:39], v[168:171], v[208:211], v[36:39]
	v_mfma_f32_16x16x32_bf16 v[32:35], v[176:179], v[208:211], v[32:35]
	v_mfma_f32_16x16x32_bf16 v[68:71], v[172:175], v[188:191], v[68:71]
	v_mfma_f32_16x16x32_bf16 v[64:67], v[180:183], v[188:191], v[64:67]
	v_mfma_f32_16x16x32_bf16 v[52:55], v[172:175], v[196:199], v[52:55]
	v_mfma_f32_16x16x32_bf16 v[48:51], v[180:183], v[196:199], v[48:51]
	v_mfma_f32_16x16x32_bf16 v[44:47], v[172:175], v[204:207], v[44:47]
	v_mfma_f32_16x16x32_bf16 v[40:43], v[180:183], v[204:207], v[40:43]
	v_mfma_f32_16x16x32_bf16 v[36:39], v[172:175], v[212:215], v[36:39]
	v_mfma_f32_16x16x32_bf16 v[32:35], v[180:183], v[212:215], v[32:35]
	s_setprio 0
	s_barrier
	s_add_i32 s20, s24, s94
	s_add_u32 s98, s28, 0x80
	s_addc_u32 s99, s29, 0
	s_mov_b32 m0, s20
	ds_read_b128 v[184:187], v155 offset:49152
	global_load_lds_dwordx4 v132, s[98:99]
	s_add_i32 m0, s20, 0x2000
	s_add_u32 s20, s28, 0x160080
	s_addc_u32 s21, s29, 0
	s_add_i32 s24, s25, s94
	global_load_lds_dwordx4 v128, s[98:99]
	s_mov_b32 m0, s24
	ds_read_b128 v[188:191], v155 offset:50176
	global_load_lds_dwordx4 v132, s[20:21]
	s_add_i32 m0, s24, 0x2000
	ds_read_b128 v[192:195], v155 offset:51200
	global_load_lds_dwordx4 v128, s[20:21]
	s_add_u32 s100, s30, 0x80
	s_addc_u32 s101, s31, 0
	s_mov_b32 m0, s36
	ds_read_b128 v[196:199], v155 offset:52224
	global_load_lds_dwordx4 v134, s[100:101]
	s_mov_b32 m0, s37
	ds_read_b128 v[200:203], v155 offset:53248
	global_load_lds_dwordx4 v130, s[100:101]
	ds_read_b128 v[204:207], v155 offset:54272
	ds_read_b128 v[208:211], v155 offset:55296
	ds_read_b128 v[212:215], v155 offset:56320
	s_waitcnt vmcnt(8)
	s_waitcnt lgkmcnt(0)
	s_barrier
	s_setprio 1
	s_waitcnt lgkmcnt(0)
	v_mfma_f32_16x16x32_bf16 v[92:95], v[144:147], v[184:187], v[92:95]
	v_mfma_f32_16x16x32_bf16 v[88:91], v[160:163], v[184:187], v[88:91]
	v_mfma_f32_16x16x32_bf16 v[84:87], v[144:147], v[192:195], v[84:87]
	v_mfma_f32_16x16x32_bf16 v[80:83], v[160:163], v[192:195], v[80:83]
	v_mfma_f32_16x16x32_bf16 v[76:79], v[144:147], v[200:203], v[76:79]
	v_mfma_f32_16x16x32_bf16 v[72:75], v[160:163], v[200:203], v[72:75]
	v_mfma_f32_16x16x32_bf16 v[60:63], v[144:147], v[208:211], v[60:63]
	v_mfma_f32_16x16x32_bf16 v[56:59], v[160:163], v[208:211], v[56:59]
	v_mfma_f32_16x16x32_bf16 v[92:95], v[156:159], v[188:191], v[92:95]
	v_mfma_f32_16x16x32_bf16 v[88:91], v[164:167], v[188:191], v[88:91]
	v_mfma_f32_16x16x32_bf16 v[84:87], v[156:159], v[196:199], v[84:87]
	v_mfma_f32_16x16x32_bf16 v[80:83], v[164:167], v[196:199], v[80:83]
	v_mfma_f32_16x16x32_bf16 v[76:79], v[156:159], v[204:207], v[76:79]
	v_mfma_f32_16x16x32_bf16 v[72:75], v[164:167], v[204:207], v[72:75]
	v_mfma_f32_16x16x32_bf16 v[60:63], v[156:159], v[212:215], v[60:63]
	v_mfma_f32_16x16x32_bf16 v[56:59], v[164:167], v[212:215], v[56:59]
	s_setprio 0
	s_setprio 1
	v_mfma_f32_16x16x32_bf16 v[28:31], v[168:171], v[184:187], v[28:31]
	v_mfma_f32_16x16x32_bf16 v[24:27], v[176:179], v[184:187], v[24:27]
	v_mfma_f32_16x16x32_bf16 v[20:23], v[168:171], v[192:195], v[20:23]
	v_mfma_f32_16x16x32_bf16 v[16:19], v[176:179], v[192:195], v[16:19]
	v_mfma_f32_16x16x32_bf16 v[12:15], v[168:171], v[200:203], v[12:15]
	v_mfma_f32_16x16x32_bf16 v[8:11], v[176:179], v[200:203], v[8:11]
	v_mfma_f32_16x16x32_bf16 v[4:7], v[168:171], v[208:211], v[4:7]
	v_mfma_f32_16x16x32_bf16 v[0:3], v[176:179], v[208:211], v[0:3]
	v_mfma_f32_16x16x32_bf16 v[28:31], v[172:175], v[188:191], v[28:31]
	v_mfma_f32_16x16x32_bf16 v[24:27], v[180:183], v[188:191], v[24:27]
	v_mfma_f32_16x16x32_bf16 v[20:23], v[172:175], v[196:199], v[20:23]
	v_mfma_f32_16x16x32_bf16 v[16:19], v[180:183], v[196:199], v[16:19]
	v_mfma_f32_16x16x32_bf16 v[12:15], v[172:175], v[204:207], v[12:15]
	v_mfma_f32_16x16x32_bf16 v[8:11], v[180:183], v[204:207], v[8:11]
	v_mfma_f32_16x16x32_bf16 v[4:7], v[172:175], v[212:215], v[4:7]
	v_mfma_f32_16x16x32_bf16 v[0:3], v[180:183], v[212:215], v[0:3]
	s_setprio 0
	s_add_i32 s45, s45, 2
	s_add_u32 s43, s43, 0x100
	s_addc_u32 s44, s44, 0
	s_cmpk_gt_u32 s45, 0x55
	s_mov_b64 s[20:21], s[26:27]
	s_barrier
	s_cbranch_scc0 .LBB0_1810
	s_and_b64 vcc, exec, s[22:23]
	s_cbranch_vccz .LBB0_1813
	s_barrier
